# baseline (speedup 1.0000x reference)
; #define PG8_STAGE(bufoff, gbase, voff) do { _Pragma("unroll") for (int _i = 0; _i < 2; ++_i) \
;         __builtin_amdgcn_global_load_lds((const unsigned*)((const char*)(gbase) + (voff)[_i]), (PG8_LAS unsigned*)(lds + (bufoff) + ldsw + _i * 8192), 16, 0, 0); } while (0)
; #define PG8_LDA(dst, b, h) do { _Pragma("unroll") for (int m = 0; m < 4; ++m) _Pragma("unroll") for (int k = 0; k < 2; ++k) dst[m][k] = *(const PG8_LAS bf16x8*)(lds + PG8_SA(b, h) + aoff + m * 2048 + k * 1024); } while (0)
; #define PG8_LDB(dst, b, h) do { _Pragma("unroll") for (int n = 0; n < 2; ++n) _Pragma("unroll") for (int k = 0; k < 2; ++k) dst[n][k] = *(const PG8_LAS bf16x8*)(lds + PG8_SB(b, h) + boff + n * 2048 + k * 1024); } while (0)
; #define PG8_MMA(ai, bj, At, Bt) do { __builtin_amdgcn_s_setprio(1); _Pragma("unroll") for (int m = 0; m < 4; ++m) _Pragma("unroll") for (int n = 0; n < 2; ++n) _Pragma("unroll") for (int k = 0; k < 2; ++k) \
;         acc[ai][bj][m][n] = __builtin_amdgcn_mfma_f32_16x16x32_bf16(Bt[n][k], At[m][k], acc[ai][bj][m][n], 0, 0, 0); __builtin_amdgcn_s_setprio(0); } while (0)
; #define PG8_WAIT_V(n) asm volatile("s_waitcnt vmcnt(" #n ")" ::: "memory")
; #define PG8_WAIT_L(n) asm volatile("s_waitcnt lgkmcnt(" #n ")" ::: "memory")
; #define PG8_BAR __builtin_amdgcn_s_barrier()
; #define PG8_SCHED __builtin_amdgcn_sched_barrier(0)
; template <class Epi, class Sched, bool ALIGN_EPI = false, bool SP2 = false>
; __device__ __forceinline__ void gemm_phase(PG8_LAS unsigned char* lds, const Gemm g, const Sched& S, const Epi& E) {
;     ...
;             PG8_LDB(B0, 0, 0); PG8_LDB(B1, 0, 1); PG8_SCHED; PG8_LDA(At, 0, 0); PG8_STAGE(PG8_SA(1, 1), a1 + hstep, voffA);
;             PG8_WAIT_V(8); PG8_WAIT_L(0); PG8_BAR; PG8_MMA(0, 0, At, B0); PG8_MMA(0, 1, At, B1); PG8_BAR; PG8_SCHED;
;             PG8_LDA(At, 0, 1); PG8_STAGE(PG8_SB(0, 0), b2, voffB); PG8_STAGE(PG8_SB(0, 1), b2 + hstep, voffB); PG8_STAGE(PG8_SA(0, 0), a2, voffA);
;             PG8_WAIT_V(8); PG8_WAIT_L(0); PG8_BAR; PG8_MMA(1, 0, At, B0); PG8_MMA(1, 1, At, B1); PG8_BAR; PG8_SCHED;
.LBB0_213:
	s_or_b32 s21, s13, 1
	s_mul_i32 s46, s35, s21
	s_mul_hi_u32 s47, s34, s21
	s_add_i32 s47, s47, s46
	s_mul_i32 s21, s34, s21
	s_add_u32 s21, s30, s21
	s_addc_u32 s59, s31, s47
	s_add_u32 s46, s44, s42
	s_addc_u32 s47, s45, s43
	s_add_i32 s66, 0, 0x10000
	v_add_u32_e32 v150, s66, v159
	s_add_i32 s76, 0, 0x14000
	ds_read_b128 v[142:145], v150
	ds_read_b128 v[146:149], v150 offset:1024
	ds_read_b128 v[162:165], v150 offset:2048
	ds_read_b128 v[166:169], v150 offset:3072
	v_add_u32_e32 v150, s76, v159
	ds_read_b128 v[170:173], v150
	ds_read_b128 v[174:177], v150 offset:1024
	ds_read_b128 v[178:181], v150 offset:2048
	ds_read_b128 v[182:185], v150 offset:3072
	s_add_u32 s68, s21, 0x40000
	s_addc_u32 s69, s59, 0
	v_lshl_add_u64 v[150:151], s[68:69], 0, v[128:129]
	s_add_i32 m0, s29, 0xc000
	ds_read_b128 v[186:189], v161
	ds_read_b128 v[190:193], v161 offset:1024
	ds_read_b128 v[198:201], v161 offset:2048
	ds_read_b128 v[202:205], v161 offset:3072
	ds_read_b128 v[206:209], v161 offset:4096
	ds_read_b128 v[210:213], v161 offset:5120
	ds_read_b128 v[214:217], v161 offset:6144
	ds_read_b128 v[218:221], v161 offset:7168
	global_load_lds_dwordx4 v[150:151], off
	v_lshl_add_u64 v[150:151], s[68:69], 0, v[132:133]
	s_add_i32 m0, s29, 0xe000
	s_nop 0
	global_load_lds_dwordx4 v[150:151], off
	s_waitcnt vmcnt(8)
	s_waitcnt lgkmcnt(0)
	s_barrier
	s_setprio 1
	s_waitcnt lgkmcnt(0)
	v_mfma_f32_16x16x32_bf16 v[124:127], v[142:145], v[186:189], v[124:127]
	v_mfma_f32_16x16x32_bf16 v[120:123], v[162:165], v[186:189], v[120:123]
	v_mfma_f32_16x16x32_bf16 v[108:111], v[142:145], v[198:201], v[108:111]
	v_mfma_f32_16x16x32_bf16 v[104:107], v[162:165], v[198:201], v[104:107]
	v_mfma_f32_16x16x32_bf16 v[92:95], v[142:145], v[206:209], v[92:95]
	v_mfma_f32_16x16x32_bf16 v[88:91], v[162:165], v[206:209], v[88:91]
	v_mfma_f32_16x16x32_bf16 v[76:79], v[142:145], v[214:217], v[76:79]
	v_mfma_f32_16x16x32_bf16 v[72:75], v[162:165], v[214:217], v[72:75]
	v_mfma_f32_16x16x32_bf16 v[124:127], v[146:149], v[190:193], v[124:127]
	v_mfma_f32_16x16x32_bf16 v[120:123], v[166:169], v[190:193], v[120:123]
	v_mfma_f32_16x16x32_bf16 v[108:111], v[146:149], v[202:205], v[108:111]
	v_mfma_f32_16x16x32_bf16 v[104:107], v[166:169], v[202:205], v[104:107]
	v_mfma_f32_16x16x32_bf16 v[92:95], v[146:149], v[210:213], v[92:95]
	v_mfma_f32_16x16x32_bf16 v[88:91], v[166:169], v[210:213], v[88:91]
	v_mfma_f32_16x16x32_bf16 v[76:79], v[146:149], v[218:221], v[76:79]
	v_mfma_f32_16x16x32_bf16 v[72:75], v[166:169], v[218:221], v[72:75]
	s_setprio 0
	s_setprio 1
	v_mfma_f32_16x16x32_bf16 v[116:119], v[170:173], v[186:189], v[116:119]
	v_mfma_f32_16x16x32_bf16 v[112:115], v[178:181], v[186:189], v[112:115]
	v_mfma_f32_16x16x32_bf16 v[100:103], v[170:173], v[198:201], v[100:103]
	v_mfma_f32_16x16x32_bf16 v[96:99], v[178:181], v[198:201], v[96:99]
	v_mfma_f32_16x16x32_bf16 v[84:87], v[170:173], v[206:209], v[84:87]
	v_mfma_f32_16x16x32_bf16 v[80:83], v[178:181], v[206:209], v[80:83]
	v_mfma_f32_16x16x32_bf16 v[68:71], v[170:173], v[214:217], v[68:71]
	v_mfma_f32_16x16x32_bf16 v[64:67], v[178:181], v[214:217], v[64:67]
	v_mfma_f32_16x16x32_bf16 v[116:119], v[174:177], v[190:193], v[116:119]
	v_mfma_f32_16x16x32_bf16 v[112:115], v[182:185], v[190:193], v[112:115]
	v_mfma_f32_16x16x32_bf16 v[100:103], v[174:177], v[202:205], v[100:103]
	v_mfma_f32_16x16x32_bf16 v[96:99], v[182:185], v[202:205], v[96:99]
	v_mfma_f32_16x16x32_bf16 v[84:87], v[174:177], v[210:213], v[84:87]
	v_mfma_f32_16x16x32_bf16 v[80:83], v[182:185], v[210:213], v[80:83]
	v_mfma_f32_16x16x32_bf16 v[68:71], v[174:177], v[218:221], v[68:71]
	v_mfma_f32_16x16x32_bf16 v[64:67], v[182:185], v[218:221], v[64:67]
	s_setprio 0
	s_barrier
	s_add_i32 s21, s66, s50
	v_lshl_add_u64 v[150:151], s[40:41], 0, v[130:131]
	s_mov_b32 m0, s21
	ds_read_b128 v[186:189], v161 offset:16384
	ds_read_b128 v[190:193], v161 offset:17408
	ds_read_b128 v[198:201], v161 offset:18432
	ds_read_b128 v[202:205], v161 offset:19456
	ds_read_b128 v[206:209], v161 offset:20480
	ds_read_b128 v[210:213], v161 offset:21504
	ds_read_b128 v[214:217], v161 offset:22528
	ds_read_b128 v[218:221], v161 offset:23552
	global_load_lds_dwordx4 v[150:151], off
	s_add_i32 m0, s21, 0x2000
	s_add_u32 s68, s40, 0x40000
	v_lshl_add_u64 v[150:151], s[40:41], 0, v[134:135]
	s_addc_u32 s69, s41, 0
	s_add_i32 s21, s76, s50
	global_load_lds_dwordx4 v[150:151], off
	v_lshl_add_u64 v[150:151], s[68:69], 0, v[130:131]
	s_mov_b32 m0, s21
	s_nop 0
	global_load_lds_dwordx4 v[150:151], off
	v_lshl_add_u64 v[150:151], s[68:69], 0, v[134:135]
	s_add_i32 m0, s21, 0x2000
	s_nop 0
	global_load_lds_dwordx4 v[150:151], off
	v_lshl_add_u64 v[150:151], s[44:45], 0, v[128:129]
	s_mov_b32 m0, s29
	s_nop 0
	global_load_lds_dwordx4 v[150:151], off
	v_lshl_add_u64 v[150:151], s[44:45], 0, v[132:133]
	s_mov_b32 m0, s51
	s_nop 0
	global_load_lds_dwordx4 v[150:151], off
	s_waitcnt vmcnt(8)
	s_waitcnt lgkmcnt(0)
	s_barrier
; #define PG8_STAGE(bufoff, gbase, voff) do { _Pragma("unroll") for (int _i = 0; _i < 2; ++_i) \
;         __builtin_amdgcn_global_load_lds((const unsigned*)((const char*)(gbase) + (voff)[_i]), (PG8_LAS unsigned*)(lds + (bufoff) + ldsw + _i * 8192), 16, 0, 0); } while (0)
; #define PG8_LDA(dst, b, h) do { _Pragma("unroll") for (int m = 0; m < 4; ++m) _Pragma("unroll") for (int k = 0; k < 2; ++k) dst[m][k] = *(const PG8_LAS bf16x8*)(lds + PG8_SA(b, h) + aoff + m * 2048 + k * 1024); } while (0)
; #define PG8_LDB(dst, b, h) do { _Pragma("unroll") for (int n = 0; n < 2; ++n) _Pragma("unroll") for (int k = 0; k < 2; ++k) dst[n][k] = *(const PG8_LAS bf16x8*)(lds + PG8_SB(b, h) + boff + n * 2048 + k * 1024); } while (0)
; #define PG8_MMA(ai, bj, At, Bt) do { __builtin_amdgcn_s_setprio(1); _Pragma("unroll") for (int m = 0; m < 4; ++m) _Pragma("unroll") for (int n = 0; n < 2; ++n) _Pragma("unroll") for (int k = 0; k < 2; ++k) \
;         acc[ai][bj][m][n] = __builtin_amdgcn_mfma_f32_16x16x32_bf16(Bt[n][k], At[m][k], acc[ai][bj][m][n], 0, 0, 0); __builtin_amdgcn_s_setprio(0); } while (0)
; #define PG8_WAIT_V(n) asm volatile("s_waitcnt vmcnt(" #n ")" ::: "memory")
; #define PG8_WAIT_L(n) asm volatile("s_waitcnt lgkmcnt(" #n ")" ::: "memory")
; #define PG8_BAR __builtin_amdgcn_s_barrier()
; #define PG8_SCHED __builtin_amdgcn_sched_barrier(0)
; template <class Epi, class Sched, bool ALIGN_EPI = false, bool SP2 = false>
; __device__ __forceinline__ void gemm_phase(PG8_LAS unsigned char* lds, const Gemm g, const Sched& S, const Epi& E) {
;     ...
;             PG8_WAIT_V(8); PG8_WAIT_L(0); PG8_BAR; PG8_MMA(1, 0, At, B0); PG8_MMA(1, 1, At, B1); PG8_BAR; PG8_SCHED;
;             PG8_LDB(B0, 1, 0); PG8_LDB(B1, 1, 1); PG8_SCHED; PG8_LDA(At, 1, 0); PG8_STAGE(PG8_SA(0, 1), a2 + hstep, voffA);
;             PG8_WAIT_V(8); PG8_WAIT_L(0); PG8_BAR; PG8_MMA(0, 0, At, B0); PG8_MMA(0, 1, At, B1); PG8_BAR; PG8_SCHED;
	s_setprio 1
	s_waitcnt lgkmcnt(0)
	v_mfma_f32_16x16x32_bf16 v[60:63], v[142:145], v[186:189], v[60:63]
	v_mfma_f32_16x16x32_bf16 v[56:59], v[162:165], v[186:189], v[56:59]
	v_mfma_f32_16x16x32_bf16 v[44:47], v[142:145], v[198:201], v[44:47]
	v_mfma_f32_16x16x32_bf16 v[40:43], v[162:165], v[198:201], v[40:43]
	v_mfma_f32_16x16x32_bf16 v[28:31], v[142:145], v[206:209], v[28:31]
	v_mfma_f32_16x16x32_bf16 v[24:27], v[162:165], v[206:209], v[24:27]
	v_mfma_f32_16x16x32_bf16 v[12:15], v[142:145], v[214:217], v[12:15]
	v_mfma_f32_16x16x32_bf16 v[8:11], v[162:165], v[214:217], v[8:11]
	v_mfma_f32_16x16x32_bf16 v[60:63], v[146:149], v[190:193], v[60:63]
	v_mfma_f32_16x16x32_bf16 v[56:59], v[166:169], v[190:193], v[56:59]
	v_mfma_f32_16x16x32_bf16 v[44:47], v[146:149], v[202:205], v[44:47]
	v_mfma_f32_16x16x32_bf16 v[40:43], v[166:169], v[202:205], v[40:43]
	v_mfma_f32_16x16x32_bf16 v[28:31], v[146:149], v[210:213], v[28:31]
	v_mfma_f32_16x16x32_bf16 v[24:27], v[166:169], v[210:213], v[24:27]
	v_mfma_f32_16x16x32_bf16 v[12:15], v[146:149], v[218:221], v[12:15]
	v_mfma_f32_16x16x32_bf16 v[8:11], v[166:169], v[218:221], v[8:11]
	s_setprio 0
	s_setprio 1
	v_mfma_f32_16x16x32_bf16 v[52:55], v[170:173], v[186:189], v[52:55]
	v_mfma_f32_16x16x32_bf16 v[48:51], v[178:181], v[186:189], v[48:51]
	v_mfma_f32_16x16x32_bf16 v[36:39], v[170:173], v[198:201], v[36:39]
	v_mfma_f32_16x16x32_bf16 v[32:35], v[178:181], v[198:201], v[32:35]
	v_mfma_f32_16x16x32_bf16 v[20:23], v[170:173], v[206:209], v[20:23]
	v_mfma_f32_16x16x32_bf16 v[16:19], v[178:181], v[206:209], v[16:19]
	v_mfma_f32_16x16x32_bf16 v[4:7], v[170:173], v[214:217], v[4:7]
	v_mfma_f32_16x16x32_bf16 v[0:3], v[178:181], v[214:217], v[0:3]
	v_mfma_f32_16x16x32_bf16 v[52:55], v[174:177], v[190:193], v[52:55]
	v_mfma_f32_16x16x32_bf16 v[48:51], v[182:185], v[190:193], v[48:51]
	v_mfma_f32_16x16x32_bf16 v[36:39], v[174:177], v[202:205], v[36:39]
	v_mfma_f32_16x16x32_bf16 v[32:35], v[182:185], v[202:205], v[32:35]
	v_mfma_f32_16x16x32_bf16 v[20:23], v[174:177], v[210:213], v[20:23]
	v_mfma_f32_16x16x32_bf16 v[16:19], v[182:185], v[210:213], v[16:19]
	v_mfma_f32_16x16x32_bf16 v[4:7], v[174:177], v[218:221], v[4:7]
	v_mfma_f32_16x16x32_bf16 v[0:3], v[182:185], v[218:221], v[0:3]
	s_setprio 0
	s_barrier
	s_add_i32 s21, 0, 0x18000
	v_add_u32_e32 v150, s21, v159
	s_add_i32 s59, 0, 0x1c000
	ds_read_b128 v[142:145], v150
	ds_read_b128 v[146:149], v150 offset:1024
	ds_read_b128 v[162:165], v150 offset:2048
	ds_read_b128 v[166:169], v150 offset:3072
	v_add_u32_e32 v150, s59, v159
	ds_read_b128 v[170:173], v150
	ds_read_b128 v[174:177], v150 offset:1024
	ds_read_b128 v[178:181], v150 offset:2048
	ds_read_b128 v[182:185], v150 offset:3072
	s_add_u32 s44, s44, 0x40000
	s_addc_u32 s45, s45, 0
	s_mov_b32 m0, s52
	v_lshl_add_u64 v[150:151], s[44:45], 0, v[128:129]
	ds_read_b128 v[186:189], v161 offset:32768
	ds_read_b128 v[190:193], v161 offset:33792
	ds_read_b128 v[198:201], v161 offset:34816
	ds_read_b128 v[202:205], v161 offset:35840
	ds_read_b128 v[206:209], v161 offset:36864
	ds_read_b128 v[210:213], v161 offset:37888
	ds_read_b128 v[214:217], v161 offset:38912
	ds_read_b128 v[218:221], v161 offset:39936
	global_load_lds_dwordx4 v[150:151], off
	v_lshl_add_u64 v[150:151], s[44:45], 0, v[132:133]
	s_mov_b32 m0, s53
	s_nop 0
	global_load_lds_dwordx4 v[150:151], off
	s_waitcnt vmcnt(8)
	s_waitcnt lgkmcnt(0)
	s_barrier
	s_setprio 1
	s_waitcnt lgkmcnt(0)
	v_mfma_f32_16x16x32_bf16 v[124:127], v[142:145], v[186:189], v[124:127]
	v_mfma_f32_16x16x32_bf16 v[120:123], v[162:165], v[186:189], v[120:123]
	v_mfma_f32_16x16x32_bf16 v[108:111], v[142:145], v[198:201], v[108:111]
	v_mfma_f32_16x16x32_bf16 v[104:107], v[162:165], v[198:201], v[104:107]
	v_mfma_f32_16x16x32_bf16 v[92:95], v[142:145], v[206:209], v[92:95]
	v_mfma_f32_16x16x32_bf16 v[88:91], v[162:165], v[206:209], v[88:91]
	v_mfma_f32_16x16x32_bf16 v[76:79], v[142:145], v[214:217], v[76:79]
	v_mfma_f32_16x16x32_bf16 v[72:75], v[162:165], v[214:217], v[72:75]
	v_mfma_f32_16x16x32_bf16 v[124:127], v[146:149], v[190:193], v[124:127]
	v_mfma_f32_16x16x32_bf16 v[120:123], v[166:169], v[190:193], v[120:123]
	v_mfma_f32_16x16x32_bf16 v[108:111], v[146:149], v[202:205], v[108:111]
	v_mfma_f32_16x16x32_bf16 v[104:107], v[166:169], v[202:205], v[104:107]
	v_mfma_f32_16x16x32_bf16 v[92:95], v[146:149], v[210:213], v[92:95]
	v_mfma_f32_16x16x32_bf16 v[88:91], v[166:169], v[210:213], v[88:91]
	v_mfma_f32_16x16x32_bf16 v[76:79], v[146:149], v[218:221], v[76:79]
	v_mfma_f32_16x16x32_bf16 v[72:75], v[166:169], v[218:221], v[72:75]
	s_setprio 0
	s_setprio 1
	v_mfma_f32_16x16x32_bf16 v[116:119], v[170:173], v[186:189], v[116:119]
	v_mfma_f32_16x16x32_bf16 v[112:115], v[178:181], v[186:189], v[112:115]
	v_mfma_f32_16x16x32_bf16 v[100:103], v[170:173], v[198:201], v[100:103]
	v_mfma_f32_16x16x32_bf16 v[96:99], v[178:181], v[198:201], v[96:99]
	v_mfma_f32_16x16x32_bf16 v[84:87], v[170:173], v[206:209], v[84:87]
	v_mfma_f32_16x16x32_bf16 v[80:83], v[178:181], v[206:209], v[80:83]
	v_mfma_f32_16x16x32_bf16 v[68:71], v[170:173], v[214:217], v[68:71]
	v_mfma_f32_16x16x32_bf16 v[64:67], v[178:181], v[214:217], v[64:67]
	v_mfma_f32_16x16x32_bf16 v[116:119], v[174:177], v[190:193], v[116:119]
	v_mfma_f32_16x16x32_bf16 v[112:115], v[182:185], v[190:193], v[112:115]
	v_mfma_f32_16x16x32_bf16 v[100:103], v[174:177], v[202:205], v[100:103]
	v_mfma_f32_16x16x32_bf16 v[96:99], v[182:185], v[202:205], v[96:99]
	v_mfma_f32_16x16x32_bf16 v[84:87], v[174:177], v[210:213], v[84:87]
	v_mfma_f32_16x16x32_bf16 v[80:83], v[182:185], v[210:213], v[80:83]
	v_mfma_f32_16x16x32_bf16 v[68:71], v[174:177], v[218:221], v[68:71]
	v_mfma_f32_16x16x32_bf16 v[64:67], v[182:185], v[218:221], v[64:67]
	s_setprio 0
	s_barrier
; #define PG8_STAGE(bufoff, gbase, voff) do { _Pragma("unroll") for (int _i = 0; _i < 2; ++_i) \
;         __builtin_amdgcn_global_load_lds((const unsigned*)((const char*)(gbase) + (voff)[_i]), (PG8_LAS unsigned*)(lds + (bufoff) + ldsw + _i * 8192), 16, 0, 0); } while (0)
; #define PG8_LDA(dst, b, h) do { _Pragma("unroll") for (int m = 0; m < 4; ++m) _Pragma("unroll") for (int k = 0; k < 2; ++k) dst[m][k] = *(const PG8_LAS bf16x8*)(lds + PG8_SA(b, h) + aoff + m * 2048 + k * 1024); } while (0)
; #define PG8_MMA(ai, bj, At, Bt) do { __builtin_amdgcn_s_setprio(1); _Pragma("unroll") for (int m = 0; m < 4; ++m) _Pragma("unroll") for (int n = 0; n < 2; ++n) _Pragma("unroll") for (int k = 0; k < 2; ++k) \
;         acc[ai][bj][m][n] = __builtin_amdgcn_mfma_f32_16x16x32_bf16(Bt[n][k], At[m][k], acc[ai][bj][m][n], 0, 0, 0); __builtin_amdgcn_s_setprio(0); } while (0)
; #define PG8_WAIT_V(n) asm volatile("s_waitcnt vmcnt(" #n ")" ::: "memory")
; #define PG8_WAIT_L(n) asm volatile("s_waitcnt lgkmcnt(" #n ")" ::: "memory")
; #define PG8_BAR __builtin_amdgcn_s_barrier()
; #define PG8_SCHED __builtin_amdgcn_sched_barrier(0)
; template <class Epi, class Sched, bool ALIGN_EPI = false, bool SP2 = false>
; __device__ __forceinline__ void gemm_phase(PG8_LAS unsigned char* lds, const Gemm g, const Sched& S, const Epi& E) {
;     ...
;         for (int t = 0; t < nt; t += 2) {
;             const bool last = (t == nt - 2);
;             const char* a1 = cA + (size_t)(t + 1) * kstep;
;             const char* a2 = last ? nA : cA + (size_t)(t + 2) * kstep; const char* b2 = last ? nB : cB + (size_t)(t + 2) * kstep;
;             const char* a3 = a2 + (last ? knext : kstep); const char* b3 = b2 + (last ? knext : kstep);
;     ...
;             PG8_LDA(At, 1, 1); PG8_STAGE(PG8_SB(1, 0), b3, voffB); PG8_STAGE(PG8_SB(1, 1), b3 + hstep, voffB); PG8_STAGE(PG8_SA(1, 0), a3, voffA);
;             PG8_WAIT_V(8); PG8_WAIT_L(0); PG8_BAR; PG8_MMA(1, 0, At, B0); PG8_MMA(1, 1, At, B1); PG8_BAR; PG8_SCHED;
	s_add_u32 s40, s40, s42
	s_addc_u32 s41, s41, s43
	s_add_i32 s21, s21, s50
	v_lshl_add_u64 v[150:151], s[40:41], 0, v[130:131]
	s_mov_b32 m0, s21
	ds_read_b128 v[186:189], v161 offset:49152
	ds_read_b128 v[190:193], v161 offset:50176
	ds_read_b128 v[198:201], v161 offset:51200
	ds_read_b128 v[202:205], v161 offset:52224
	ds_read_b128 v[206:209], v161 offset:53248
	ds_read_b128 v[210:213], v161 offset:54272
	ds_read_b128 v[214:217], v161 offset:55296
	ds_read_b128 v[218:221], v161 offset:56320
	global_load_lds_dwordx4 v[150:151], off
	s_add_i32 m0, s21, 0x2000
	v_lshl_add_u64 v[150:151], s[40:41], 0, v[134:135]
	s_add_u32 s40, s40, 0x40000
	s_addc_u32 s41, s41, 0
	s_add_i32 s21, s59, s50
	global_load_lds_dwordx4 v[150:151], off
	v_lshl_add_u64 v[150:151], s[40:41], 0, v[130:131]
	s_mov_b32 m0, s21
	s_nop 0
	global_load_lds_dwordx4 v[150:151], off
	v_lshl_add_u64 v[150:151], s[40:41], 0, v[134:135]
	s_add_i32 m0, s21, 0x2000
	s_nop 0
	global_load_lds_dwordx4 v[150:151], off
	v_lshl_add_u64 v[150:151], s[46:47], 0, v[128:129]
	s_mov_b32 m0, s55
	s_nop 0
	global_load_lds_dwordx4 v[150:151], off
	v_lshl_add_u64 v[150:151], s[46:47], 0, v[132:133]
	s_mov_b32 m0, s56
	s_nop 0
	global_load_lds_dwordx4 v[150:151], off
	s_waitcnt vmcnt(8)
	s_waitcnt lgkmcnt(0)
	s_barrier
	s_setprio 1
	s_waitcnt lgkmcnt(0)
	v_mfma_f32_16x16x32_bf16 v[60:63], v[142:145], v[186:189], v[60:63]
	v_mfma_f32_16x16x32_bf16 v[56:59], v[162:165], v[186:189], v[56:59]
	v_mfma_f32_16x16x32_bf16 v[44:47], v[142:145], v[198:201], v[44:47]
	v_mfma_f32_16x16x32_bf16 v[40:43], v[162:165], v[198:201], v[40:43]
	v_mfma_f32_16x16x32_bf16 v[28:31], v[142:145], v[206:209], v[28:31]
	v_mfma_f32_16x16x32_bf16 v[24:27], v[162:165], v[206:209], v[24:27]
	v_mfma_f32_16x16x32_bf16 v[12:15], v[142:145], v[214:217], v[12:15]
	v_mfma_f32_16x16x32_bf16 v[8:11], v[162:165], v[214:217], v[8:11]
	v_mfma_f32_16x16x32_bf16 v[60:63], v[146:149], v[190:193], v[60:63]
	v_mfma_f32_16x16x32_bf16 v[56:59], v[166:169], v[190:193], v[56:59]
	v_mfma_f32_16x16x32_bf16 v[44:47], v[146:149], v[202:205], v[44:47]
	v_mfma_f32_16x16x32_bf16 v[40:43], v[166:169], v[202:205], v[40:43]
	v_mfma_f32_16x16x32_bf16 v[28:31], v[146:149], v[210:213], v[28:31]
	v_mfma_f32_16x16x32_bf16 v[24:27], v[166:169], v[210:213], v[24:27]
	v_mfma_f32_16x16x32_bf16 v[12:15], v[146:149], v[218:221], v[12:15]
	v_mfma_f32_16x16x32_bf16 v[8:11], v[166:169], v[218:221], v[8:11]
	s_setprio 0
	s_setprio 1
	v_mfma_f32_16x16x32_bf16 v[52:55], v[170:173], v[186:189], v[52:55]
	v_mfma_f32_16x16x32_bf16 v[48:51], v[178:181], v[186:189], v[48:51]
	v_mfma_f32_16x16x32_bf16 v[36:39], v[170:173], v[198:201], v[36:39]
	v_mfma_f32_16x16x32_bf16 v[32:35], v[178:181], v[198:201], v[32:35]
	v_mfma_f32_16x16x32_bf16 v[20:23], v[170:173], v[206:209], v[20:23]
	v_mfma_f32_16x16x32_bf16 v[16:19], v[178:181], v[206:209], v[16:19]
	v_mfma_f32_16x16x32_bf16 v[4:7], v[170:173], v[214:217], v[4:7]
	v_mfma_f32_16x16x32_bf16 v[0:3], v[178:181], v[214:217], v[0:3]
	v_mfma_f32_16x16x32_bf16 v[52:55], v[174:177], v[190:193], v[52:55]
	v_mfma_f32_16x16x32_bf16 v[48:51], v[182:185], v[190:193], v[48:51]
	v_mfma_f32_16x16x32_bf16 v[36:39], v[174:177], v[202:205], v[36:39]
	v_mfma_f32_16x16x32_bf16 v[32:35], v[182:185], v[202:205], v[32:35]
	v_mfma_f32_16x16x32_bf16 v[20:23], v[174:177], v[210:213], v[20:23]
	v_mfma_f32_16x16x32_bf16 v[16:19], v[182:185], v[210:213], v[16:19]
	v_mfma_f32_16x16x32_bf16 v[4:7], v[174:177], v[218:221], v[4:7]
	v_mfma_f32_16x16x32_bf16 v[0:3], v[182:185], v[218:221], v[0:3]
	s_setprio 0
	s_cmp_gt_u32 s13, 13
	s_mov_b32 s13, s19
	s_cbranch_scc1 .Lrot_r214_exit
	s_cmp_lg_u32 s13, 14
	s_cselect_b64 s[40:41], -1, 0
	s_cmp_eq_u32 s13, 14
	s_mov_b64 s[44:45], s[36:37]
	s_cbranch_scc1 .Lrot_r214_216
	s_add_i32 s19, s13, 2
	s_mul_i32 s21, s35, s19
	s_mul_hi_u32 s42, s34, s19
	s_add_i32 s42, s42, s21
	s_mul_i32 s19, s34, s19
	s_add_u32 s44, s30, s19
	s_addc_u32 s45, s31, s42

; #define PG8_MMA(ai, bj, At, Bt) do { __builtin_amdgcn_s_setprio(1); _Pragma("unroll") for (int m = 0; m < 4; ++m) _Pragma("unroll") for (int n = 0; n < 2; ++n) _Pragma("unroll") for (int k = 0; k < 2; ++k) \
;         acc[ai][bj][m][n] = __builtin_amdgcn_mfma_f32_16x16x32_bf16(Bt[n][k], At[m][k], acc[ai][bj][m][n], 0, 0, 0); __builtin_amdgcn_s_setprio(0); } while (0)
; #define PG8_WAIT_V(n) asm volatile("s_waitcnt vmcnt(" #n ")" ::: "memory")
; #define PG8_WAIT_L(n) asm volatile("s_waitcnt lgkmcnt(" #n ")" ::: "memory")
; #define PG8_BAR __builtin_amdgcn_s_barrier()
; #define PG8_SCHED __builtin_amdgcn_sched_barrier(0)
; template <class Epi, class Sched, bool ALIGN_EPI = false, bool SP2 = false>
; __device__ __forceinline__ void gemm_phase(PG8_LAS unsigned char* lds, const Gemm g, const Sched& S, const Epi& E) {
;     ...
;             PG8_WAIT_V(8); PG8_WAIT_L(0); PG8_BAR; PG8_MMA(1, 0, At, B0); PG8_MMA(1, 1, At, B1); PG8_BAR; PG8_SCHED;
.Lrot_r214_bar:
	s_barrier
	s_branch .LBB0_213

; #define PG8_STAGE(bufoff, gbase, voff) do { _Pragma("unroll") for (int _i = 0; _i < 2; ++_i) \
;         __builtin_amdgcn_global_load_lds((const unsigned*)((const char*)(gbase) + (voff)[_i]), (PG8_LAS unsigned*)(lds + (bufoff) + ldsw + _i * 8192), 16, 0, 0); } while (0)
; #define PG8_LDA(dst, b, h) do { _Pragma("unroll") for (int m = 0; m < 4; ++m) _Pragma("unroll") for (int k = 0; k < 2; ++k) dst[m][k] = *(const PG8_LAS bf16x8*)(lds + PG8_SA(b, h) + aoff + m * 2048 + k * 1024); } while (0)
; #define PG8_LDB(dst, b, h) do { _Pragma("unroll") for (int n = 0; n < 2; ++n) _Pragma("unroll") for (int k = 0; k < 2; ++k) dst[n][k] = *(const PG8_LAS bf16x8*)(lds + PG8_SB(b, h) + boff + n * 2048 + k * 1024); } while (0)
; #define PG8_MMA(ai, bj, At, Bt) do { __builtin_amdgcn_s_setprio(1); _Pragma("unroll") for (int m = 0; m < 4; ++m) _Pragma("unroll") for (int n = 0; n < 2; ++n) _Pragma("unroll") for (int k = 0; k < 2; ++k) \
;         acc[ai][bj][m][n] = __builtin_amdgcn_mfma_f32_16x16x32_bf16(Bt[n][k], At[m][k], acc[ai][bj][m][n], 0, 0, 0); __builtin_amdgcn_s_setprio(0); } while (0)
; #define PG8_WAIT_V(n) asm volatile("s_waitcnt vmcnt(" #n ")" ::: "memory")
; #define PG8_WAIT_L(n) asm volatile("s_waitcnt lgkmcnt(" #n ")" ::: "memory")
; #define PG8_BAR __builtin_amdgcn_s_barrier()
; #define PG8_SCHED __builtin_amdgcn_sched_barrier(0)
; template <class Epi, class Sched, bool ALIGN_EPI = false, bool SP2 = false>
; __device__ __forceinline__ void gemm_phase(PG8_LAS unsigned char* lds, const Gemm g, const Sched& S, const Epi& E) {
;     ...
;             PG8_LDB(B0, 0, 0); PG8_LDB(B1, 0, 1); PG8_SCHED; PG8_LDA(At, 0, 0); PG8_STAGE(PG8_SA(1, 1), a1 + hstep, voffA);
;             PG8_WAIT_V(8); PG8_WAIT_L(0); PG8_BAR; PG8_MMA(0, 0, At, B0); PG8_MMA(0, 1, At, B1); PG8_BAR; PG8_SCHED;
;             PG8_LDA(At, 0, 1); PG8_STAGE(PG8_SB(0, 0), b2, voffB); PG8_STAGE(PG8_SB(0, 1), b2 + hstep, voffB); PG8_STAGE(PG8_SA(0, 0), a2, voffA);
;             PG8_WAIT_V(8); PG8_WAIT_L(0); PG8_BAR; PG8_MMA(1, 0, At, B0); PG8_MMA(1, 1, At, B1); PG8_BAR; PG8_SCHED;
.LBB0_531:
	s_add_i32 s59, s59, 2
	s_add_u32 s48, s46, s44
	s_addc_u32 s49, s47, s45
	s_add_i32 s66, 0, 0x10000
	s_add_i32 s92, 0, 0x14000
	v_add_u32_e32 v144, s66, v185
	v_add_u32_e32 v178, s92, v185
	ds_read_b128 v[100:103], v144
	ds_read_b128 v[104:107], v144 offset:1024
	ds_read_b128 v[112:115], v144 offset:2048
	ds_read_b128 v[144:147], v144 offset:3072
	ds_read_b128 v[148:151], v178
	ds_read_b128 v[170:173], v178 offset:1024
	ds_read_b128 v[174:177], v178 offset:2048
	ds_read_b128 v[178:181], v178 offset:3072
	v_lshl_add_u64 v[182:183], v[92:93], 0, s[40:41]
	s_add_i32 m0, s55, 0xc000
	ds_read_b128 v[188:191], v187
	ds_read_b128 v[198:201], v187 offset:1024
	ds_read_b128 v[202:205], v187 offset:2048
	ds_read_b128 v[206:209], v187 offset:3072
	ds_read_b128 v[210:213], v187 offset:4096
	ds_read_b128 v[214:217], v187 offset:5120
	ds_read_b128 v[218:221], v187 offset:6144
	ds_read_b128 v[222:225], v187 offset:7168
	global_load_lds_dwordx4 v[182:183], off
	v_lshl_add_u64 v[182:183], v[94:95], 0, s[40:41]
	s_add_i32 m0, s55, 0xe000
	s_nop 0
	global_load_lds_dwordx4 v[182:183], off
	s_waitcnt vmcnt(8)
	s_waitcnt lgkmcnt(0)
	s_barrier
	s_setprio 1
	s_waitcnt lgkmcnt(0)
	v_mfma_f32_16x16x32_bf16 v[140:143], v[100:103], v[188:191], v[140:143]
	v_mfma_f32_16x16x32_bf16 v[136:139], v[112:115], v[188:191], v[136:139]
	v_mfma_f32_16x16x32_bf16 v[124:127], v[100:103], v[202:205], v[124:127]
	v_mfma_f32_16x16x32_bf16 v[120:123], v[112:115], v[202:205], v[120:123]
	v_mfma_f32_16x16x32_bf16 v[96:99], v[100:103], v[210:213], v[96:99]
	v_mfma_f32_16x16x32_bf16 v[88:91], v[112:115], v[210:213], v[88:91]
	v_mfma_f32_16x16x32_bf16 v[76:79], v[100:103], v[218:221], v[76:79]
	v_mfma_f32_16x16x32_bf16 v[72:75], v[112:115], v[218:221], v[72:75]
	v_mfma_f32_16x16x32_bf16 v[140:143], v[104:107], v[198:201], v[140:143]
	v_mfma_f32_16x16x32_bf16 v[136:139], v[144:147], v[198:201], v[136:139]
	v_mfma_f32_16x16x32_bf16 v[124:127], v[104:107], v[206:209], v[124:127]
	v_mfma_f32_16x16x32_bf16 v[120:123], v[144:147], v[206:209], v[120:123]
	v_mfma_f32_16x16x32_bf16 v[96:99], v[104:107], v[214:217], v[96:99]
	v_mfma_f32_16x16x32_bf16 v[88:91], v[144:147], v[214:217], v[88:91]
	v_mfma_f32_16x16x32_bf16 v[76:79], v[104:107], v[222:225], v[76:79]
	v_mfma_f32_16x16x32_bf16 v[72:75], v[144:147], v[222:225], v[72:75]
	s_setprio 0
	s_setprio 1
	v_mfma_f32_16x16x32_bf16 v[132:135], v[148:151], v[188:191], v[132:135]
	v_mfma_f32_16x16x32_bf16 v[128:131], v[174:177], v[188:191], v[128:131]
	v_mfma_f32_16x16x32_bf16 v[116:119], v[148:151], v[202:205], v[116:119]
	v_mfma_f32_16x16x32_bf16 v[108:111], v[174:177], v[202:205], v[108:111]
	v_mfma_f32_16x16x32_bf16 v[84:87], v[148:151], v[210:213], v[84:87]
	v_mfma_f32_16x16x32_bf16 v[80:83], v[174:177], v[210:213], v[80:83]
	v_mfma_f32_16x16x32_bf16 v[68:71], v[148:151], v[218:221], v[68:71]
	v_mfma_f32_16x16x32_bf16 v[64:67], v[174:177], v[218:221], v[64:67]
	v_mfma_f32_16x16x32_bf16 v[132:135], v[170:173], v[198:201], v[132:135]
	v_mfma_f32_16x16x32_bf16 v[128:131], v[178:181], v[198:201], v[128:131]
	v_mfma_f32_16x16x32_bf16 v[116:119], v[170:173], v[206:209], v[116:119]
	v_mfma_f32_16x16x32_bf16 v[108:111], v[178:181], v[206:209], v[108:111]
	v_mfma_f32_16x16x32_bf16 v[84:87], v[170:173], v[214:217], v[84:87]
	v_mfma_f32_16x16x32_bf16 v[80:83], v[178:181], v[214:217], v[80:83]
	v_mfma_f32_16x16x32_bf16 v[68:71], v[170:173], v[222:225], v[68:71]
	v_mfma_f32_16x16x32_bf16 v[64:67], v[178:181], v[222:225], v[64:67]
	s_setprio 0
	s_barrier
	s_add_i32 s66, s66, s52
	v_lshl_add_u64 v[182:183], s[42:43], 0, v[154:155]
	s_mov_b32 m0, s66
	ds_read_b128 v[188:191], v187 offset:16384
	ds_read_b128 v[198:201], v187 offset:17408
	ds_read_b128 v[202:205], v187 offset:18432
	ds_read_b128 v[206:209], v187 offset:19456
	ds_read_b128 v[210:213], v187 offset:20480
	ds_read_b128 v[214:217], v187 offset:21504
	ds_read_b128 v[218:221], v187 offset:22528
	ds_read_b128 v[222:225], v187 offset:23552
	global_load_lds_dwordx4 v[182:183], off
	s_add_i32 m0, s66, 0x2000
	s_add_u32 s76, s42, 0x40000
	v_lshl_add_u64 v[182:183], s[42:43], 0, v[164:165]
	s_addc_u32 s77, s43, 0
	s_add_i32 s66, s92, s52
	global_load_lds_dwordx4 v[182:183], off
	v_lshl_add_u64 v[182:183], s[76:77], 0, v[154:155]
	s_mov_b32 m0, s66
	s_nop 0
	global_load_lds_dwordx4 v[182:183], off
	v_lshl_add_u64 v[182:183], s[76:77], 0, v[164:165]
	s_add_i32 m0, s66, 0x2000
	s_nop 0
	global_load_lds_dwordx4 v[182:183], off
	v_lshl_add_u64 v[182:183], s[46:47], 0, v[160:161]
	s_mov_b32 m0, s55
	s_nop 0
	global_load_lds_dwordx4 v[182:183], off
	v_lshl_add_u64 v[182:183], s[46:47], 0, v[162:163]
	s_mov_b32 m0, s56
	s_nop 0
	global_load_lds_dwordx4 v[182:183], off
	s_waitcnt vmcnt(8)
	s_waitcnt lgkmcnt(0)
	s_barrier
; #define PG8_STAGE(bufoff, gbase, voff) do { _Pragma("unroll") for (int _i = 0; _i < 2; ++_i) \
;         __builtin_amdgcn_global_load_lds((const unsigned*)((const char*)(gbase) + (voff)[_i]), (PG8_LAS unsigned*)(lds + (bufoff) + ldsw + _i * 8192), 16, 0, 0); } while (0)
; #define PG8_LDA(dst, b, h) do { _Pragma("unroll") for (int m = 0; m < 4; ++m) _Pragma("unroll") for (int k = 0; k < 2; ++k) dst[m][k] = *(const PG8_LAS bf16x8*)(lds + PG8_SA(b, h) + aoff + m * 2048 + k * 1024); } while (0)
; #define PG8_LDB(dst, b, h) do { _Pragma("unroll") for (int n = 0; n < 2; ++n) _Pragma("unroll") for (int k = 0; k < 2; ++k) dst[n][k] = *(const PG8_LAS bf16x8*)(lds + PG8_SB(b, h) + boff + n * 2048 + k * 1024); } while (0)
; #define PG8_MMA(ai, bj, At, Bt) do { __builtin_amdgcn_s_setprio(1); _Pragma("unroll") for (int m = 0; m < 4; ++m) _Pragma("unroll") for (int n = 0; n < 2; ++n) _Pragma("unroll") for (int k = 0; k < 2; ++k) \
;         acc[ai][bj][m][n] = __builtin_amdgcn_mfma_f32_16x16x32_bf16(Bt[n][k], At[m][k], acc[ai][bj][m][n], 0, 0, 0); __builtin_amdgcn_s_setprio(0); } while (0)
; #define PG8_WAIT_V(n) asm volatile("s_waitcnt vmcnt(" #n ")" ::: "memory")
; #define PG8_WAIT_L(n) asm volatile("s_waitcnt lgkmcnt(" #n ")" ::: "memory")
; #define PG8_BAR __builtin_amdgcn_s_barrier()
; #define PG8_SCHED __builtin_amdgcn_sched_barrier(0)
; template <class Epi, class Sched, bool ALIGN_EPI = false, bool SP2 = false>
; __device__ __forceinline__ void gemm_phase(PG8_LAS unsigned char* lds, const Gemm g, const Sched& S, const Epi& E) {
;     ...
;             PG8_WAIT_V(8); PG8_WAIT_L(0); PG8_BAR; PG8_MMA(1, 0, At, B0); PG8_MMA(1, 1, At, B1); PG8_BAR; PG8_SCHED;
;             PG8_LDB(B0, 1, 0); PG8_LDB(B1, 1, 1); PG8_SCHED; PG8_LDA(At, 1, 0); PG8_STAGE(PG8_SA(0, 1), a2 + hstep, voffA);
;             PG8_WAIT_V(8); PG8_WAIT_L(0); PG8_BAR; PG8_MMA(0, 0, At, B0); PG8_MMA(0, 1, At, B1); PG8_BAR; PG8_SCHED;
	s_setprio 1
	s_waitcnt lgkmcnt(0)
	v_mfma_f32_16x16x32_bf16 v[60:63], v[100:103], v[188:191], v[60:63]
	v_mfma_f32_16x16x32_bf16 v[56:59], v[112:115], v[188:191], v[56:59]
	v_mfma_f32_16x16x32_bf16 v[44:47], v[100:103], v[202:205], v[44:47]
	v_mfma_f32_16x16x32_bf16 v[40:43], v[112:115], v[202:205], v[40:43]
	v_mfma_f32_16x16x32_bf16 v[28:31], v[100:103], v[210:213], v[28:31]
	v_mfma_f32_16x16x32_bf16 v[24:27], v[112:115], v[210:213], v[24:27]
	v_mfma_f32_16x16x32_bf16 v[12:15], v[100:103], v[218:221], v[12:15]
	v_mfma_f32_16x16x32_bf16 v[8:11], v[112:115], v[218:221], v[8:11]
	v_mfma_f32_16x16x32_bf16 v[60:63], v[104:107], v[198:201], v[60:63]
	v_mfma_f32_16x16x32_bf16 v[56:59], v[144:147], v[198:201], v[56:59]
	v_mfma_f32_16x16x32_bf16 v[44:47], v[104:107], v[206:209], v[44:47]
	v_mfma_f32_16x16x32_bf16 v[40:43], v[144:147], v[206:209], v[40:43]
	v_mfma_f32_16x16x32_bf16 v[28:31], v[104:107], v[214:217], v[28:31]
	v_mfma_f32_16x16x32_bf16 v[24:27], v[144:147], v[214:217], v[24:27]
	v_mfma_f32_16x16x32_bf16 v[12:15], v[104:107], v[222:225], v[12:15]
	v_mfma_f32_16x16x32_bf16 v[8:11], v[144:147], v[222:225], v[8:11]
	s_setprio 0
	s_setprio 1
	v_mfma_f32_16x16x32_bf16 v[52:55], v[148:151], v[188:191], v[52:55]
	v_mfma_f32_16x16x32_bf16 v[48:51], v[174:177], v[188:191], v[48:51]
	v_mfma_f32_16x16x32_bf16 v[36:39], v[148:151], v[202:205], v[36:39]
	v_mfma_f32_16x16x32_bf16 v[32:35], v[174:177], v[202:205], v[32:35]
	v_mfma_f32_16x16x32_bf16 v[20:23], v[148:151], v[210:213], v[20:23]
	v_mfma_f32_16x16x32_bf16 v[16:19], v[174:177], v[210:213], v[16:19]
	v_mfma_f32_16x16x32_bf16 v[4:7], v[148:151], v[218:221], v[4:7]
	v_mfma_f32_16x16x32_bf16 v[0:3], v[174:177], v[218:221], v[0:3]
	v_mfma_f32_16x16x32_bf16 v[52:55], v[170:173], v[198:201], v[52:55]
	v_mfma_f32_16x16x32_bf16 v[48:51], v[178:181], v[198:201], v[48:51]
	v_mfma_f32_16x16x32_bf16 v[36:39], v[170:173], v[206:209], v[36:39]
	v_mfma_f32_16x16x32_bf16 v[32:35], v[178:181], v[206:209], v[32:35]
	v_mfma_f32_16x16x32_bf16 v[20:23], v[170:173], v[214:217], v[20:23]
	v_mfma_f32_16x16x32_bf16 v[16:19], v[178:181], v[214:217], v[16:19]
	v_mfma_f32_16x16x32_bf16 v[4:7], v[170:173], v[222:225], v[4:7]
	v_mfma_f32_16x16x32_bf16 v[0:3], v[178:181], v[222:225], v[0:3]
	s_setprio 0
	s_barrier
	s_add_i32 s66, 0, 0x18000
	s_add_i32 s76, 0, 0x1c000
	v_add_u32_e32 v144, s66, v185
	v_add_u32_e32 v178, s76, v185
	ds_read_b128 v[100:103], v144
	ds_read_b128 v[104:107], v144 offset:1024
	ds_read_b128 v[112:115], v144 offset:2048
	ds_read_b128 v[144:147], v144 offset:3072
	ds_read_b128 v[148:151], v178
	ds_read_b128 v[170:173], v178 offset:1024
	ds_read_b128 v[174:177], v178 offset:2048
	ds_read_b128 v[178:181], v178 offset:3072
	s_add_u32 s46, s46, 0x40000
	s_addc_u32 s47, s47, 0
	s_mov_b32 m0, s57
	v_lshl_add_u64 v[182:183], s[46:47], 0, v[160:161]
	ds_read_b128 v[188:191], v187 offset:32768
	ds_read_b128 v[198:201], v187 offset:33792
	ds_read_b128 v[202:205], v187 offset:34816
	ds_read_b128 v[206:209], v187 offset:35840
	ds_read_b128 v[210:213], v187 offset:36864
	ds_read_b128 v[214:217], v187 offset:37888
	ds_read_b128 v[218:221], v187 offset:38912
	ds_read_b128 v[222:225], v187 offset:39936
	global_load_lds_dwordx4 v[182:183], off
	v_lshl_add_u64 v[182:183], s[46:47], 0, v[162:163]
	s_mov_b32 m0, s60
	s_nop 0
	global_load_lds_dwordx4 v[182:183], off
	s_waitcnt vmcnt(8)
	s_waitcnt lgkmcnt(0)
	s_barrier
	s_setprio 1
	s_waitcnt lgkmcnt(0)
	v_mfma_f32_16x16x32_bf16 v[140:143], v[100:103], v[188:191], v[140:143]
	v_mfma_f32_16x16x32_bf16 v[136:139], v[112:115], v[188:191], v[136:139]
	v_mfma_f32_16x16x32_bf16 v[124:127], v[100:103], v[202:205], v[124:127]
	v_mfma_f32_16x16x32_bf16 v[120:123], v[112:115], v[202:205], v[120:123]
	v_mfma_f32_16x16x32_bf16 v[96:99], v[100:103], v[210:213], v[96:99]
	v_mfma_f32_16x16x32_bf16 v[88:91], v[112:115], v[210:213], v[88:91]
	v_mfma_f32_16x16x32_bf16 v[76:79], v[100:103], v[218:221], v[76:79]
	v_mfma_f32_16x16x32_bf16 v[72:75], v[112:115], v[218:221], v[72:75]
	v_mfma_f32_16x16x32_bf16 v[140:143], v[104:107], v[198:201], v[140:143]
	v_mfma_f32_16x16x32_bf16 v[136:139], v[144:147], v[198:201], v[136:139]
	v_mfma_f32_16x16x32_bf16 v[124:127], v[104:107], v[206:209], v[124:127]
	v_mfma_f32_16x16x32_bf16 v[120:123], v[144:147], v[206:209], v[120:123]
	v_mfma_f32_16x16x32_bf16 v[96:99], v[104:107], v[214:217], v[96:99]
	v_mfma_f32_16x16x32_bf16 v[88:91], v[144:147], v[214:217], v[88:91]
	v_mfma_f32_16x16x32_bf16 v[76:79], v[104:107], v[222:225], v[76:79]
	v_mfma_f32_16x16x32_bf16 v[72:75], v[144:147], v[222:225], v[72:75]
	s_setprio 0
	s_setprio 1
	v_mfma_f32_16x16x32_bf16 v[132:135], v[148:151], v[188:191], v[132:135]
	v_mfma_f32_16x16x32_bf16 v[128:131], v[174:177], v[188:191], v[128:131]
	v_mfma_f32_16x16x32_bf16 v[116:119], v[148:151], v[202:205], v[116:119]
	v_mfma_f32_16x16x32_bf16 v[108:111], v[174:177], v[202:205], v[108:111]
	v_mfma_f32_16x16x32_bf16 v[84:87], v[148:151], v[210:213], v[84:87]
	v_mfma_f32_16x16x32_bf16 v[80:83], v[174:177], v[210:213], v[80:83]
	v_mfma_f32_16x16x32_bf16 v[68:71], v[148:151], v[218:221], v[68:71]
	v_mfma_f32_16x16x32_bf16 v[64:67], v[174:177], v[218:221], v[64:67]
	v_mfma_f32_16x16x32_bf16 v[132:135], v[170:173], v[198:201], v[132:135]
	v_mfma_f32_16x16x32_bf16 v[128:131], v[178:181], v[198:201], v[128:131]
	v_mfma_f32_16x16x32_bf16 v[116:119], v[170:173], v[206:209], v[116:119]
	v_mfma_f32_16x16x32_bf16 v[108:111], v[178:181], v[206:209], v[108:111]
	v_mfma_f32_16x16x32_bf16 v[84:87], v[170:173], v[214:217], v[84:87]
	v_mfma_f32_16x16x32_bf16 v[80:83], v[178:181], v[214:217], v[80:83]
	v_mfma_f32_16x16x32_bf16 v[68:71], v[170:173], v[222:225], v[68:71]
	v_mfma_f32_16x16x32_bf16 v[64:67], v[178:181], v[222:225], v[64:67]
	s_setprio 0
	s_barrier
; #define PG8_STAGE(bufoff, gbase, voff) do { _Pragma("unroll") for (int _i = 0; _i < 2; ++_i) \
;         __builtin_amdgcn_global_load_lds((const unsigned*)((const char*)(gbase) + (voff)[_i]), (PG8_LAS unsigned*)(lds + (bufoff) + ldsw + _i * 8192), 16, 0, 0); } while (0)
; #define PG8_LDA(dst, b, h) do { _Pragma("unroll") for (int m = 0; m < 4; ++m) _Pragma("unroll") for (int k = 0; k < 2; ++k) dst[m][k] = *(const PG8_LAS bf16x8*)(lds + PG8_SA(b, h) + aoff + m * 2048 + k * 1024); } while (0)
; #define PG8_MMA(ai, bj, At, Bt) do { __builtin_amdgcn_s_setprio(1); _Pragma("unroll") for (int m = 0; m < 4; ++m) _Pragma("unroll") for (int n = 0; n < 2; ++n) _Pragma("unroll") for (int k = 0; k < 2; ++k) \
;         acc[ai][bj][m][n] = __builtin_amdgcn_mfma_f32_16x16x32_bf16(Bt[n][k], At[m][k], acc[ai][bj][m][n], 0, 0, 0); __builtin_amdgcn_s_setprio(0); } while (0)
; #define PG8_WAIT_V(n) asm volatile("s_waitcnt vmcnt(" #n ")" ::: "memory")
; #define PG8_WAIT_L(n) asm volatile("s_waitcnt lgkmcnt(" #n ")" ::: "memory")
; #define PG8_BAR __builtin_amdgcn_s_barrier()
; #define PG8_SCHED __builtin_amdgcn_sched_barrier(0)
; template <class Epi, class Sched, bool ALIGN_EPI = false, bool SP2 = false>
; __device__ __forceinline__ void gemm_phase(PG8_LAS unsigned char* lds, const Gemm g, const Sched& S, const Epi& E) {
;     ...
;         for (int t = 0; t < nt; t += 2) {
;             const bool last = (t == nt - 2);
;             const char* a1 = cA + (size_t)(t + 1) * kstep;
;             const char* a2 = last ? nA : cA + (size_t)(t + 2) * kstep; const char* b2 = last ? nB : cB + (size_t)(t + 2) * kstep;
;             const char* a3 = a2 + (last ? knext : kstep); const char* b3 = b2 + (last ? knext : kstep);
;     ...
;             PG8_LDA(At, 1, 1); PG8_STAGE(PG8_SB(1, 0), b3, voffB); PG8_STAGE(PG8_SB(1, 1), b3 + hstep, voffB); PG8_STAGE(PG8_SA(1, 0), a3, voffA);
;             PG8_WAIT_V(8); PG8_WAIT_L(0); PG8_BAR; PG8_MMA(1, 0, At, B0); PG8_MMA(1, 1, At, B1); PG8_BAR; PG8_SCHED;
	s_add_u32 s42, s42, s44
	s_addc_u32 s43, s43, s45
	s_add_i32 s44, s66, s52
	v_lshl_add_u64 v[182:183], s[42:43], 0, v[154:155]
	s_mov_b32 m0, s44
	ds_read_b128 v[188:191], v187 offset:49152
	ds_read_b128 v[198:201], v187 offset:50176
	ds_read_b128 v[202:205], v187 offset:51200
	ds_read_b128 v[206:209], v187 offset:52224
	ds_read_b128 v[210:213], v187 offset:53248
	ds_read_b128 v[214:217], v187 offset:54272
	ds_read_b128 v[218:221], v187 offset:55296
	ds_read_b128 v[222:225], v187 offset:56320
	global_load_lds_dwordx4 v[182:183], off
	s_add_i32 m0, s44, 0x2000
	v_lshl_add_u64 v[182:183], s[42:43], 0, v[164:165]
	s_add_u32 s42, s42, 0x40000
	s_addc_u32 s43, s43, 0
	s_add_i32 s44, s76, s52
	global_load_lds_dwordx4 v[182:183], off
	v_lshl_add_u64 v[182:183], s[42:43], 0, v[154:155]
	s_mov_b32 m0, s44
	s_nop 0
	global_load_lds_dwordx4 v[182:183], off
	v_lshl_add_u64 v[182:183], s[42:43], 0, v[164:165]
	s_add_i32 m0, s44, 0x2000
	s_nop 0
	global_load_lds_dwordx4 v[182:183], off
	v_lshl_add_u64 v[182:183], s[48:49], 0, v[160:161]
	s_mov_b32 m0, s63
	s_nop 0
	global_load_lds_dwordx4 v[182:183], off
	v_lshl_add_u64 v[182:183], s[48:49], 0, v[162:163]
	s_mov_b32 m0, s65
	s_nop 0
	global_load_lds_dwordx4 v[182:183], off
	s_waitcnt vmcnt(8)
	s_waitcnt lgkmcnt(0)
	s_barrier
	s_setprio 1
	s_waitcnt lgkmcnt(0)
	v_mfma_f32_16x16x32_bf16 v[60:63], v[100:103], v[188:191], v[60:63]
	v_mfma_f32_16x16x32_bf16 v[56:59], v[112:115], v[188:191], v[56:59]
	v_mfma_f32_16x16x32_bf16 v[44:47], v[100:103], v[202:205], v[44:47]
	v_mfma_f32_16x16x32_bf16 v[40:43], v[112:115], v[202:205], v[40:43]
	v_mfma_f32_16x16x32_bf16 v[28:31], v[100:103], v[210:213], v[28:31]
	v_mfma_f32_16x16x32_bf16 v[24:27], v[112:115], v[210:213], v[24:27]
	v_mfma_f32_16x16x32_bf16 v[12:15], v[100:103], v[218:221], v[12:15]
	v_mfma_f32_16x16x32_bf16 v[8:11], v[112:115], v[218:221], v[8:11]
	v_mfma_f32_16x16x32_bf16 v[60:63], v[104:107], v[198:201], v[60:63]
	v_mfma_f32_16x16x32_bf16 v[56:59], v[144:147], v[198:201], v[56:59]
	v_mfma_f32_16x16x32_bf16 v[44:47], v[104:107], v[206:209], v[44:47]
	v_mfma_f32_16x16x32_bf16 v[40:43], v[144:147], v[206:209], v[40:43]
	v_mfma_f32_16x16x32_bf16 v[28:31], v[104:107], v[214:217], v[28:31]
	v_mfma_f32_16x16x32_bf16 v[24:27], v[144:147], v[214:217], v[24:27]
	v_mfma_f32_16x16x32_bf16 v[12:15], v[104:107], v[222:225], v[12:15]
	v_mfma_f32_16x16x32_bf16 v[8:11], v[144:147], v[222:225], v[8:11]
	s_setprio 0
	s_setprio 1
	v_mfma_f32_16x16x32_bf16 v[52:55], v[148:151], v[188:191], v[52:55]
	v_mfma_f32_16x16x32_bf16 v[48:51], v[174:177], v[188:191], v[48:51]
	v_mfma_f32_16x16x32_bf16 v[36:39], v[148:151], v[202:205], v[36:39]
	v_mfma_f32_16x16x32_bf16 v[32:35], v[174:177], v[202:205], v[32:35]
	v_mfma_f32_16x16x32_bf16 v[20:23], v[148:151], v[210:213], v[20:23]
	v_mfma_f32_16x16x32_bf16 v[16:19], v[174:177], v[210:213], v[16:19]
	v_mfma_f32_16x16x32_bf16 v[4:7], v[148:151], v[218:221], v[4:7]
	v_mfma_f32_16x16x32_bf16 v[0:3], v[174:177], v[218:221], v[0:3]
	v_mfma_f32_16x16x32_bf16 v[52:55], v[170:173], v[198:201], v[52:55]
	v_mfma_f32_16x16x32_bf16 v[48:51], v[178:181], v[198:201], v[48:51]
	v_mfma_f32_16x16x32_bf16 v[36:39], v[170:173], v[206:209], v[36:39]
	v_mfma_f32_16x16x32_bf16 v[32:35], v[178:181], v[206:209], v[32:35]
	v_mfma_f32_16x16x32_bf16 v[20:23], v[170:173], v[214:217], v[20:23]
	v_mfma_f32_16x16x32_bf16 v[16:19], v[178:181], v[214:217], v[16:19]
	v_mfma_f32_16x16x32_bf16 v[4:7], v[170:173], v[222:225], v[4:7]
	v_mfma_f32_16x16x32_bf16 v[0:3], v[178:181], v[222:225], v[0:3]
	s_setprio 0
	s_add_u32 s40, s40, s38
	s_addc_u32 s41, s41, s39
	s_cmp_ge_i32 s59, s1
	s_cbranch_scc1 .Lrot_r532_exit
	s_cmp_lg_u32 s9, s59
	s_cselect_b64 s[42:43], -1, 0
	s_cmp_eq_u32 s9, s59
	s_mov_b64 s[46:47], s[24:25]
	s_cbranch_scc1 .Lrot_r532_534
	s_add_u32 s46, s19, s40
	s_addc_u32 s47, s21, s41

; #define PG8_STAGE(bufoff, gbase, voff) do { _Pragma("unroll") for (int _i = 0; _i < 2; ++_i) \
;         __builtin_amdgcn_global_load_lds((const unsigned*)((const char*)(gbase) + (voff)[_i]), (PG8_LAS unsigned*)(lds + (bufoff) + ldsw + _i * 8192), 16, 0, 0); } while (0)
; #define PG8_LDA(dst, b, h) do { _Pragma("unroll") for (int m = 0; m < 4; ++m) _Pragma("unroll") for (int k = 0; k < 2; ++k) dst[m][k] = *(const PG8_LAS bf16x8*)(lds + PG8_SA(b, h) + aoff + m * 2048 + k * 1024); } while (0)
; #define PG8_LDB(dst, b, h) do { _Pragma("unroll") for (int n = 0; n < 2; ++n) _Pragma("unroll") for (int k = 0; k < 2; ++k) dst[n][k] = *(const PG8_LAS bf16x8*)(lds + PG8_SB(b, h) + boff + n * 2048 + k * 1024); } while (0)
; #define PG8_MMA(ai, bj, At, Bt) do { __builtin_amdgcn_s_setprio(1); _Pragma("unroll") for (int m = 0; m < 4; ++m) _Pragma("unroll") for (int n = 0; n < 2; ++n) _Pragma("unroll") for (int k = 0; k < 2; ++k) \
;         acc[ai][bj][m][n] = __builtin_amdgcn_mfma_f32_16x16x32_bf16(Bt[n][k], At[m][k], acc[ai][bj][m][n], 0, 0, 0); __builtin_amdgcn_s_setprio(0); } while (0)
; #define PG8_WAIT_V(n) asm volatile("s_waitcnt vmcnt(" #n ")" ::: "memory")
; #define PG8_WAIT_L(n) asm volatile("s_waitcnt lgkmcnt(" #n ")" ::: "memory")
; #define PG8_BAR __builtin_amdgcn_s_barrier()
; #define PG8_SCHED __builtin_amdgcn_sched_barrier(0)
; template <class Epi, class Sched, bool ALIGN_EPI = false, bool SP2 = false>
; __device__ __forceinline__ void gemm_phase(PG8_LAS unsigned char* lds, const Gemm g, const Sched& S, const Epi& E) {
;     ...
;         for (int t = 0; t < nt; t += 2) {
;             const bool last = (t == nt - 2);
;             const char* a1 = cA + (size_t)(t + 1) * kstep;
;             const char* a2 = last ? nA : cA + (size_t)(t + 2) * kstep; const char* b2 = last ? nB : cB + (size_t)(t + 2) * kstep;
;             const char* a3 = a2 + (last ? knext : kstep); const char* b3 = b2 + (last ? knext : kstep);
;             if (last && has_next) S.a_ready(nxt);
;             if constexpr (SP2) {
;             PG8_LDB(B0, 0, 0); PG8_LDB(B1, 0, 1); PG8_SCHED; PG8_LDA(At, 0, 0); PG8_STAGE(PG8_SA(1, 1), a1 + hstep, voffA);
;             PG8_WAIT_V(8); PG8_WAIT_L(0); PG8_BAR; PG8_MMA(0, 0, At, B0); PG8_MMA(0, 1, At, B1); PG8_BAR; PG8_SCHED;
.LBB0_799:
	s_or_b32 s44, s15, 1
	s_mul_i32 s45, s31, s44
	s_mul_hi_u32 s57, s30, s44
	s_add_i32 s57, s57, s45
	s_mul_i32 s44, s30, s44
	s_add_u32 s59, s28, s44
	s_addc_u32 s57, s29, s57
	s_add_u32 s44, s42, s40
	s_addc_u32 s45, s43, s41
	s_add_i32 s62, 0, 0x10000
	v_add_u32_e32 v134, s62, v137
	s_add_i32 s63, 0, 0x14000
	ds_read_b128 v[140:143], v134
	ds_read_b128 v[144:147], v134 offset:1024
	ds_read_b128 v[148:151], v134 offset:2048
	ds_read_b128 v[158:161], v134 offset:3072
	v_add_u32_e32 v134, s63, v137
	ds_read_b128 v[162:165], v134
	ds_read_b128 v[166:169], v134 offset:1024
	ds_read_b128 v[170:173], v134 offset:2048
	ds_read_b128 v[174:177], v134 offset:3072
	s_add_u32 s60, s59, 0x40000
	s_addc_u32 s61, s57, 0
	v_lshl_add_u64 v[134:135], s[60:61], 0, v[132:133]
	s_add_i32 m0, s23, 0xc000
	ds_read_b128 v[178:181], v139
	ds_read_b128 v[182:185], v139 offset:1024
	ds_read_b128 v[186:189], v139 offset:2048
	ds_read_b128 v[190:193], v139 offset:3072
	ds_read_b128 v[198:201], v139 offset:4096
	ds_read_b128 v[202:205], v139 offset:5120
	ds_read_b128 v[206:209], v139 offset:6144
	ds_read_b128 v[210:213], v139 offset:7168
	global_load_lds_dwordx4 v[134:135], off
	v_lshl_add_u64 v[134:135], s[60:61], 0, v[130:131]
	s_add_i32 m0, s23, 0xe000
	s_nop 0
	global_load_lds_dwordx4 v[134:135], off
	s_waitcnt vmcnt(8)
	s_waitcnt lgkmcnt(0)
	s_barrier
	s_setprio 1
	s_waitcnt lgkmcnt(0)
	v_mfma_f32_16x16x32_bf16 v[124:127], v[140:143], v[178:181], v[124:127]
	v_mfma_f32_16x16x32_bf16 v[120:123], v[148:151], v[178:181], v[120:123]
	v_mfma_f32_16x16x32_bf16 v[108:111], v[140:143], v[186:189], v[108:111]
	v_mfma_f32_16x16x32_bf16 v[104:107], v[148:151], v[186:189], v[104:107]
	v_mfma_f32_16x16x32_bf16 v[92:95], v[140:143], v[198:201], v[92:95]
	v_mfma_f32_16x16x32_bf16 v[88:91], v[148:151], v[198:201], v[88:91]
	v_mfma_f32_16x16x32_bf16 v[76:79], v[140:143], v[206:209], v[76:79]
	v_mfma_f32_16x16x32_bf16 v[72:75], v[148:151], v[206:209], v[72:75]
	v_mfma_f32_16x16x32_bf16 v[124:127], v[144:147], v[182:185], v[124:127]
	v_mfma_f32_16x16x32_bf16 v[120:123], v[158:161], v[182:185], v[120:123]
	v_mfma_f32_16x16x32_bf16 v[108:111], v[144:147], v[190:193], v[108:111]
	v_mfma_f32_16x16x32_bf16 v[104:107], v[158:161], v[190:193], v[104:107]
	v_mfma_f32_16x16x32_bf16 v[92:95], v[144:147], v[202:205], v[92:95]
	v_mfma_f32_16x16x32_bf16 v[88:91], v[158:161], v[202:205], v[88:91]
	v_mfma_f32_16x16x32_bf16 v[76:79], v[144:147], v[210:213], v[76:79]
	v_mfma_f32_16x16x32_bf16 v[72:75], v[158:161], v[210:213], v[72:75]
	s_setprio 0
	s_setprio 1
	v_mfma_f32_16x16x32_bf16 v[116:119], v[162:165], v[178:181], v[116:119]
	v_mfma_f32_16x16x32_bf16 v[112:115], v[170:173], v[178:181], v[112:115]
	v_mfma_f32_16x16x32_bf16 v[100:103], v[162:165], v[186:189], v[100:103]
	v_mfma_f32_16x16x32_bf16 v[96:99], v[170:173], v[186:189], v[96:99]
	v_mfma_f32_16x16x32_bf16 v[84:87], v[162:165], v[198:201], v[84:87]
	v_mfma_f32_16x16x32_bf16 v[80:83], v[170:173], v[198:201], v[80:83]
	v_mfma_f32_16x16x32_bf16 v[68:71], v[162:165], v[206:209], v[68:71]
	v_mfma_f32_16x16x32_bf16 v[64:67], v[170:173], v[206:209], v[64:67]
	v_mfma_f32_16x16x32_bf16 v[116:119], v[166:169], v[182:185], v[116:119]
	v_mfma_f32_16x16x32_bf16 v[112:115], v[174:177], v[182:185], v[112:115]
	v_mfma_f32_16x16x32_bf16 v[100:103], v[166:169], v[190:193], v[100:103]
	v_mfma_f32_16x16x32_bf16 v[96:99], v[174:177], v[190:193], v[96:99]
	v_mfma_f32_16x16x32_bf16 v[84:87], v[166:169], v[202:205], v[84:87]
	v_mfma_f32_16x16x32_bf16 v[80:83], v[174:177], v[202:205], v[80:83]
	v_mfma_f32_16x16x32_bf16 v[68:71], v[166:169], v[210:213], v[68:71]
	v_mfma_f32_16x16x32_bf16 v[64:67], v[174:177], v[210:213], v[64:67]
	s_setprio 0
	s_barrier
	s_add_i32 s57, s62, s51
	v_lshl_add_u64 v[134:135], s[38:39], 0, v[154:155]
	s_mov_b32 m0, s57
	ds_read_b128 v[178:181], v139 offset:16384
	ds_read_b128 v[182:185], v139 offset:17408
	ds_read_b128 v[186:189], v139 offset:18432
	ds_read_b128 v[190:193], v139 offset:19456
	ds_read_b128 v[198:201], v139 offset:20480
	ds_read_b128 v[202:205], v139 offset:21504
	ds_read_b128 v[206:209], v139 offset:22528
	ds_read_b128 v[210:213], v139 offset:23552
	global_load_lds_dwordx4 v[134:135], off
	s_add_i32 m0, s57, 0x2000
	s_add_u32 s60, s38, 0x40000
	v_lshl_add_u64 v[134:135], s[38:39], 0, v[128:129]
	s_addc_u32 s61, s39, 0
	s_add_i32 s57, s63, s51
	global_load_lds_dwordx4 v[134:135], off
	v_lshl_add_u64 v[134:135], s[60:61], 0, v[154:155]
	s_mov_b32 m0, s57
	s_nop 0
	global_load_lds_dwordx4 v[134:135], off
	v_lshl_add_u64 v[134:135], s[60:61], 0, v[128:129]
	s_add_i32 m0, s57, 0x2000
	s_nop 0
	global_load_lds_dwordx4 v[134:135], off
	v_lshl_add_u64 v[134:135], s[42:43], 0, v[132:133]
	s_mov_b32 m0, s23
	s_nop 0
	global_load_lds_dwordx4 v[134:135], off
	v_lshl_add_u64 v[134:135], s[42:43], 0, v[130:131]
	s_mov_b32 m0, s25
	s_nop 0
	global_load_lds_dwordx4 v[134:135], off
	s_waitcnt vmcnt(8)
	s_waitcnt lgkmcnt(0)
	s_barrier
; #define PG8_STAGE(bufoff, gbase, voff) do { _Pragma("unroll") for (int _i = 0; _i < 2; ++_i) \
;         __builtin_amdgcn_global_load_lds((const unsigned*)((const char*)(gbase) + (voff)[_i]), (PG8_LAS unsigned*)(lds + (bufoff) + ldsw + _i * 8192), 16, 0, 0); } while (0)
; #define PG8_LDA(dst, b, h) do { _Pragma("unroll") for (int m = 0; m < 4; ++m) _Pragma("unroll") for (int k = 0; k < 2; ++k) dst[m][k] = *(const PG8_LAS bf16x8*)(lds + PG8_SA(b, h) + aoff + m * 2048 + k * 1024); } while (0)
; #define PG8_LDB(dst, b, h) do { _Pragma("unroll") for (int n = 0; n < 2; ++n) _Pragma("unroll") for (int k = 0; k < 2; ++k) dst[n][k] = *(const PG8_LAS bf16x8*)(lds + PG8_SB(b, h) + boff + n * 2048 + k * 1024); } while (0)
; #define PG8_MMA(ai, bj, At, Bt) do { __builtin_amdgcn_s_setprio(1); _Pragma("unroll") for (int m = 0; m < 4; ++m) _Pragma("unroll") for (int n = 0; n < 2; ++n) _Pragma("unroll") for (int k = 0; k < 2; ++k) \
;         acc[ai][bj][m][n] = __builtin_amdgcn_mfma_f32_16x16x32_bf16(Bt[n][k], At[m][k], acc[ai][bj][m][n], 0, 0, 0); __builtin_amdgcn_s_setprio(0); } while (0)
; #define PG8_WAIT_V(n) asm volatile("s_waitcnt vmcnt(" #n ")" ::: "memory")
; #define PG8_WAIT_L(n) asm volatile("s_waitcnt lgkmcnt(" #n ")" ::: "memory")
; #define PG8_BAR __builtin_amdgcn_s_barrier()
; #define PG8_SCHED __builtin_amdgcn_sched_barrier(0)
; template <class Epi, class Sched, bool ALIGN_EPI = false, bool SP2 = false>
; __device__ __forceinline__ void gemm_phase(PG8_LAS unsigned char* lds, const Gemm g, const Sched& S, const Epi& E) {
;     ...
;             PG8_WAIT_V(8); PG8_WAIT_L(0); PG8_BAR; PG8_MMA(0, 0, At, B0); PG8_MMA(0, 1, At, B1); PG8_BAR; PG8_SCHED;
;             PG8_LDA(At, 0, 1); PG8_STAGE(PG8_SB(0, 0), b2, voffB); PG8_STAGE(PG8_SB(0, 1), b2 + hstep, voffB); PG8_STAGE(PG8_SA(0, 0), a2, voffA);
;             PG8_WAIT_V(8); PG8_WAIT_L(0); PG8_BAR; PG8_MMA(1, 0, At, B0); PG8_MMA(1, 1, At, B1); PG8_BAR; PG8_SCHED;
;             PG8_LDB(B0, 1, 0); PG8_LDB(B1, 1, 1); PG8_SCHED; PG8_LDA(At, 1, 0); PG8_STAGE(PG8_SA(0, 1), a2 + hstep, voffA);
;             PG8_WAIT_V(8); PG8_WAIT_L(0); PG8_BAR; PG8_MMA(0, 0, At, B0); PG8_MMA(0, 1, At, B1); PG8_BAR; PG8_SCHED;
	s_setprio 1
	s_waitcnt lgkmcnt(0)
	v_mfma_f32_16x16x32_bf16 v[60:63], v[140:143], v[178:181], v[60:63]
	v_mfma_f32_16x16x32_bf16 v[56:59], v[148:151], v[178:181], v[56:59]
	v_mfma_f32_16x16x32_bf16 v[44:47], v[140:143], v[186:189], v[44:47]
	v_mfma_f32_16x16x32_bf16 v[40:43], v[148:151], v[186:189], v[40:43]
	v_mfma_f32_16x16x32_bf16 v[28:31], v[140:143], v[198:201], v[28:31]
	v_mfma_f32_16x16x32_bf16 v[24:27], v[148:151], v[198:201], v[24:27]
	v_mfma_f32_16x16x32_bf16 v[12:15], v[140:143], v[206:209], v[12:15]
	v_mfma_f32_16x16x32_bf16 v[8:11], v[148:151], v[206:209], v[8:11]
	v_mfma_f32_16x16x32_bf16 v[60:63], v[144:147], v[182:185], v[60:63]
	v_mfma_f32_16x16x32_bf16 v[56:59], v[158:161], v[182:185], v[56:59]
	v_mfma_f32_16x16x32_bf16 v[44:47], v[144:147], v[190:193], v[44:47]
	v_mfma_f32_16x16x32_bf16 v[40:43], v[158:161], v[190:193], v[40:43]
	v_mfma_f32_16x16x32_bf16 v[28:31], v[144:147], v[202:205], v[28:31]
	v_mfma_f32_16x16x32_bf16 v[24:27], v[158:161], v[202:205], v[24:27]
	v_mfma_f32_16x16x32_bf16 v[12:15], v[144:147], v[210:213], v[12:15]
	v_mfma_f32_16x16x32_bf16 v[8:11], v[158:161], v[210:213], v[8:11]
	s_setprio 0
	s_setprio 1
	v_mfma_f32_16x16x32_bf16 v[52:55], v[162:165], v[178:181], v[52:55]
	v_mfma_f32_16x16x32_bf16 v[48:51], v[170:173], v[178:181], v[48:51]
	v_mfma_f32_16x16x32_bf16 v[36:39], v[162:165], v[186:189], v[36:39]
	v_mfma_f32_16x16x32_bf16 v[32:35], v[170:173], v[186:189], v[32:35]
	v_mfma_f32_16x16x32_bf16 v[20:23], v[162:165], v[198:201], v[20:23]
	v_mfma_f32_16x16x32_bf16 v[16:19], v[170:173], v[198:201], v[16:19]
	v_mfma_f32_16x16x32_bf16 v[4:7], v[162:165], v[206:209], v[4:7]
	v_mfma_f32_16x16x32_bf16 v[0:3], v[170:173], v[206:209], v[0:3]
	v_mfma_f32_16x16x32_bf16 v[52:55], v[166:169], v[182:185], v[52:55]
	v_mfma_f32_16x16x32_bf16 v[48:51], v[174:177], v[182:185], v[48:51]
	v_mfma_f32_16x16x32_bf16 v[36:39], v[166:169], v[190:193], v[36:39]
	v_mfma_f32_16x16x32_bf16 v[32:35], v[174:177], v[190:193], v[32:35]
	v_mfma_f32_16x16x32_bf16 v[20:23], v[166:169], v[202:205], v[20:23]
	v_mfma_f32_16x16x32_bf16 v[16:19], v[174:177], v[202:205], v[16:19]
	v_mfma_f32_16x16x32_bf16 v[4:7], v[166:169], v[210:213], v[4:7]
	v_mfma_f32_16x16x32_bf16 v[0:3], v[174:177], v[210:213], v[0:3]
	s_setprio 0
	s_barrier
	s_add_i32 s57, 0, 0x18000
	v_add_u32_e32 v134, s57, v137
	s_add_i32 s59, 0, 0x1c000
	ds_read_b128 v[140:143], v134
	ds_read_b128 v[144:147], v134 offset:1024
	ds_read_b128 v[148:151], v134 offset:2048
	ds_read_b128 v[158:161], v134 offset:3072
	v_add_u32_e32 v134, s59, v137
	ds_read_b128 v[162:165], v134
	ds_read_b128 v[166:169], v134 offset:1024
	ds_read_b128 v[170:173], v134 offset:2048
	ds_read_b128 v[174:177], v134 offset:3072
	s_add_u32 s42, s42, 0x40000
	s_addc_u32 s43, s43, 0
	s_mov_b32 m0, s52
	v_lshl_add_u64 v[134:135], s[42:43], 0, v[132:133]
	ds_read_b128 v[178:181], v139 offset:32768
	ds_read_b128 v[182:185], v139 offset:33792
	ds_read_b128 v[186:189], v139 offset:34816
	ds_read_b128 v[190:193], v139 offset:35840
	ds_read_b128 v[198:201], v139 offset:36864
	ds_read_b128 v[202:205], v139 offset:37888
	ds_read_b128 v[206:209], v139 offset:38912
	ds_read_b128 v[210:213], v139 offset:39936
	global_load_lds_dwordx4 v[134:135], off
	v_lshl_add_u64 v[134:135], s[42:43], 0, v[130:131]
	s_mov_b32 m0, s53
	s_nop 0
	global_load_lds_dwordx4 v[134:135], off
	s_waitcnt vmcnt(8)
	s_waitcnt lgkmcnt(0)
	s_barrier
	s_setprio 1
	s_waitcnt lgkmcnt(0)
	v_mfma_f32_16x16x32_bf16 v[124:127], v[140:143], v[178:181], v[124:127]
	v_mfma_f32_16x16x32_bf16 v[120:123], v[148:151], v[178:181], v[120:123]
	v_mfma_f32_16x16x32_bf16 v[108:111], v[140:143], v[186:189], v[108:111]
	v_mfma_f32_16x16x32_bf16 v[104:107], v[148:151], v[186:189], v[104:107]
	v_mfma_f32_16x16x32_bf16 v[92:95], v[140:143], v[198:201], v[92:95]
	v_mfma_f32_16x16x32_bf16 v[88:91], v[148:151], v[198:201], v[88:91]
	v_mfma_f32_16x16x32_bf16 v[76:79], v[140:143], v[206:209], v[76:79]
	v_mfma_f32_16x16x32_bf16 v[72:75], v[148:151], v[206:209], v[72:75]
	v_mfma_f32_16x16x32_bf16 v[124:127], v[144:147], v[182:185], v[124:127]
	v_mfma_f32_16x16x32_bf16 v[120:123], v[158:161], v[182:185], v[120:123]
	v_mfma_f32_16x16x32_bf16 v[108:111], v[144:147], v[190:193], v[108:111]
	v_mfma_f32_16x16x32_bf16 v[104:107], v[158:161], v[190:193], v[104:107]
	v_mfma_f32_16x16x32_bf16 v[92:95], v[144:147], v[202:205], v[92:95]
	v_mfma_f32_16x16x32_bf16 v[88:91], v[158:161], v[202:205], v[88:91]
	v_mfma_f32_16x16x32_bf16 v[76:79], v[144:147], v[210:213], v[76:79]
	v_mfma_f32_16x16x32_bf16 v[72:75], v[158:161], v[210:213], v[72:75]
	s_setprio 0
	s_setprio 1
	v_mfma_f32_16x16x32_bf16 v[116:119], v[162:165], v[178:181], v[116:119]
	v_mfma_f32_16x16x32_bf16 v[112:115], v[170:173], v[178:181], v[112:115]
	v_mfma_f32_16x16x32_bf16 v[100:103], v[162:165], v[186:189], v[100:103]
	v_mfma_f32_16x16x32_bf16 v[96:99], v[170:173], v[186:189], v[96:99]
	v_mfma_f32_16x16x32_bf16 v[84:87], v[162:165], v[198:201], v[84:87]
	v_mfma_f32_16x16x32_bf16 v[80:83], v[170:173], v[198:201], v[80:83]
	v_mfma_f32_16x16x32_bf16 v[68:71], v[162:165], v[206:209], v[68:71]
	v_mfma_f32_16x16x32_bf16 v[64:67], v[170:173], v[206:209], v[64:67]
	v_mfma_f32_16x16x32_bf16 v[116:119], v[166:169], v[182:185], v[116:119]
	v_mfma_f32_16x16x32_bf16 v[112:115], v[174:177], v[182:185], v[112:115]
	v_mfma_f32_16x16x32_bf16 v[100:103], v[166:169], v[190:193], v[100:103]
	v_mfma_f32_16x16x32_bf16 v[96:99], v[174:177], v[190:193], v[96:99]
	v_mfma_f32_16x16x32_bf16 v[84:87], v[166:169], v[202:205], v[84:87]
	v_mfma_f32_16x16x32_bf16 v[80:83], v[174:177], v[202:205], v[80:83]
	v_mfma_f32_16x16x32_bf16 v[68:71], v[166:169], v[210:213], v[68:71]
	v_mfma_f32_16x16x32_bf16 v[64:67], v[174:177], v[210:213], v[64:67]
	s_setprio 0
	s_barrier
; #define PG8_STAGE(bufoff, gbase, voff) do { _Pragma("unroll") for (int _i = 0; _i < 2; ++_i) \
;         __builtin_amdgcn_global_load_lds((const unsigned*)((const char*)(gbase) + (voff)[_i]), (PG8_LAS unsigned*)(lds + (bufoff) + ldsw + _i * 8192), 16, 0, 0); } while (0)
; #define PG8_LDA(dst, b, h) do { _Pragma("unroll") for (int m = 0; m < 4; ++m) _Pragma("unroll") for (int k = 0; k < 2; ++k) dst[m][k] = *(const PG8_LAS bf16x8*)(lds + PG8_SA(b, h) + aoff + m * 2048 + k * 1024); } while (0)
; #define PG8_WAIT_V(n) asm volatile("s_waitcnt vmcnt(" #n ")" ::: "memory")
; #define PG8_WAIT_L(n) asm volatile("s_waitcnt lgkmcnt(" #n ")" ::: "memory")
; template <class Epi, class Sched, bool ALIGN_EPI = false, bool SP2 = false>
; __device__ __forceinline__ void gemm_phase(PG8_LAS unsigned char* lds, const Gemm g, const Sched& S, const Epi& E) {
;     ...
;         for (int t = 0; t < nt; t += 2) {
;             const bool last = (t == nt - 2);
;             const char* a1 = cA + (size_t)(t + 1) * kstep;
;             const char* a2 = last ? nA : cA + (size_t)(t + 2) * kstep; const char* b2 = last ? nB : cB + (size_t)(t + 2) * kstep;
;             const char* a3 = a2 + (last ? knext : kstep); const char* b3 = b2 + (last ? knext : kstep);
;             if (last && has_next) S.a_ready(nxt);
;             if constexpr (SP2) {
;             PG8_LDB(B0, 0, 0); PG8_LDB(B1, 0, 1); PG8_SCHED; PG8_LDA(At, 0, 0); PG8_STAGE(PG8_SA(1, 1), a1 + hstep, voffA);
;             PG8_WAIT_V(8); PG8_WAIT_L(0); PG8_BAR; PG8_MMA(0, 0, At, B0); PG8_MMA(0, 1, At, B1); PG8_BAR; PG8_SCHED;
;             PG8_LDA(At, 0, 1); PG8_STAGE(PG8_SB(0, 0), b2, voffB); PG8_STAGE(PG8_SB(0, 1), b2 + hstep, voffB); PG8_STAGE(PG8_SA(0, 0), a2, voffA);
;             PG8_WAIT_V(8); PG8_WAIT_L(0); PG8_BAR; PG8_MMA(1, 0, At, B0); PG8_MMA(1, 1, At, B1); PG8_BAR; PG8_SCHED;
;             PG8_LDB(B0, 1, 0); PG8_LDB(B1, 1, 1); PG8_SCHED; PG8_LDA(At, 1, 0); PG8_STAGE(PG8_SA(0, 1), a2 + hstep, voffA);
;             PG8_WAIT_V(8); PG8_WAIT_L(0); PG8_BAR; PG8_MMA(0, 0, At, B0); PG8_MMA(0, 1, At, B1); PG8_BAR; PG8_SCHED;
;             PG8_LDA(At, 1, 1); PG8_STAGE(PG8_SB(1, 0), b3, voffB); PG8_STAGE(PG8_SB(1, 1), b3 + hstep, voffB); PG8_STAGE(PG8_SA(1, 0), a3, voffA);
;             PG8_WAIT_V(8); PG8_WAIT_L(0); PG8_BAR; PG8_MMA(1, 0, At, B0); PG8_MMA(1, 1, At, B1); PG8_BAR; PG8_SCHED;
	s_add_u32 s38, s38, s40
	s_addc_u32 s39, s39, s41
	s_add_i32 s40, s57, s51
	v_lshl_add_u64 v[134:135], s[38:39], 0, v[154:155]
	s_mov_b32 m0, s40
	ds_read_b128 v[178:181], v139 offset:49152
	ds_read_b128 v[182:185], v139 offset:50176
	ds_read_b128 v[186:189], v139 offset:51200
	ds_read_b128 v[190:193], v139 offset:52224
	ds_read_b128 v[198:201], v139 offset:53248
	ds_read_b128 v[202:205], v139 offset:54272
	ds_read_b128 v[206:209], v139 offset:55296
	ds_read_b128 v[210:213], v139 offset:56320
	global_load_lds_dwordx4 v[134:135], off
	s_add_i32 m0, s40, 0x2000
	v_lshl_add_u64 v[134:135], s[38:39], 0, v[128:129]
	s_add_u32 s38, s38, 0x40000
	s_addc_u32 s39, s39, 0
	s_add_i32 s40, s59, s51
	global_load_lds_dwordx4 v[134:135], off
	v_lshl_add_u64 v[134:135], s[38:39], 0, v[154:155]
	s_mov_b32 m0, s40
	s_nop 0
	global_load_lds_dwordx4 v[134:135], off
	v_lshl_add_u64 v[134:135], s[38:39], 0, v[128:129]
	s_add_i32 m0, s40, 0x2000
	s_nop 0
	global_load_lds_dwordx4 v[134:135], off
	v_lshl_add_u64 v[134:135], s[44:45], 0, v[132:133]
	s_mov_b32 m0, s54
	s_nop 0
	global_load_lds_dwordx4 v[134:135], off
	v_lshl_add_u64 v[134:135], s[44:45], 0, v[130:131]
	s_mov_b32 m0, s55
	s_nop 0
	global_load_lds_dwordx4 v[134:135], off
	s_waitcnt vmcnt(8)
	s_waitcnt lgkmcnt(0)
	s_barrier
	s_setprio 1
	s_waitcnt lgkmcnt(0)
	v_mfma_f32_16x16x32_bf16 v[60:63], v[140:143], v[178:181], v[60:63]
	v_mfma_f32_16x16x32_bf16 v[56:59], v[148:151], v[178:181], v[56:59]
	v_mfma_f32_16x16x32_bf16 v[44:47], v[140:143], v[186:189], v[44:47]
	v_mfma_f32_16x16x32_bf16 v[40:43], v[148:151], v[186:189], v[40:43]
	v_mfma_f32_16x16x32_bf16 v[28:31], v[140:143], v[198:201], v[28:31]
	v_mfma_f32_16x16x32_bf16 v[24:27], v[148:151], v[198:201], v[24:27]
	v_mfma_f32_16x16x32_bf16 v[12:15], v[140:143], v[206:209], v[12:15]
	v_mfma_f32_16x16x32_bf16 v[8:11], v[148:151], v[206:209], v[8:11]
	v_mfma_f32_16x16x32_bf16 v[60:63], v[144:147], v[182:185], v[60:63]
	v_mfma_f32_16x16x32_bf16 v[56:59], v[158:161], v[182:185], v[56:59]
	v_mfma_f32_16x16x32_bf16 v[44:47], v[144:147], v[190:193], v[44:47]
	v_mfma_f32_16x16x32_bf16 v[40:43], v[158:161], v[190:193], v[40:43]
	v_mfma_f32_16x16x32_bf16 v[28:31], v[144:147], v[202:205], v[28:31]
	v_mfma_f32_16x16x32_bf16 v[24:27], v[158:161], v[202:205], v[24:27]
	v_mfma_f32_16x16x32_bf16 v[12:15], v[144:147], v[210:213], v[12:15]
	v_mfma_f32_16x16x32_bf16 v[8:11], v[158:161], v[210:213], v[8:11]
	s_setprio 0
	s_setprio 1
	v_mfma_f32_16x16x32_bf16 v[52:55], v[162:165], v[178:181], v[52:55]
	v_mfma_f32_16x16x32_bf16 v[48:51], v[170:173], v[178:181], v[48:51]
	v_mfma_f32_16x16x32_bf16 v[36:39], v[162:165], v[186:189], v[36:39]
	v_mfma_f32_16x16x32_bf16 v[32:35], v[170:173], v[186:189], v[32:35]
	v_mfma_f32_16x16x32_bf16 v[20:23], v[162:165], v[198:201], v[20:23]
	v_mfma_f32_16x16x32_bf16 v[16:19], v[170:173], v[198:201], v[16:19]
	v_mfma_f32_16x16x32_bf16 v[4:7], v[162:165], v[206:209], v[4:7]
	v_mfma_f32_16x16x32_bf16 v[0:3], v[170:173], v[206:209], v[0:3]
	v_mfma_f32_16x16x32_bf16 v[52:55], v[166:169], v[182:185], v[52:55]
	v_mfma_f32_16x16x32_bf16 v[48:51], v[174:177], v[182:185], v[48:51]
	v_mfma_f32_16x16x32_bf16 v[36:39], v[166:169], v[190:193], v[36:39]
	v_mfma_f32_16x16x32_bf16 v[32:35], v[174:177], v[190:193], v[32:35]
	v_mfma_f32_16x16x32_bf16 v[20:23], v[166:169], v[202:205], v[20:23]
	v_mfma_f32_16x16x32_bf16 v[16:19], v[174:177], v[202:205], v[16:19]
	v_mfma_f32_16x16x32_bf16 v[4:7], v[166:169], v[210:213], v[4:7]
	v_mfma_f32_16x16x32_bf16 v[0:3], v[174:177], v[210:213], v[0:3]
	s_setprio 0
	s_cmp_gt_u32 s15, 13
	s_mov_b32 s15, s13
	s_cbranch_scc1 .Lrot_r800_exit
	s_cmp_lg_u32 s15, 14
	s_cselect_b64 s[38:39], -1, 0
	s_cmp_eq_u32 s15, 14
	s_mov_b64 s[42:43], s[34:35]
	s_cbranch_scc1 .Lrot_r800_802
	s_add_i32 s13, s15, 2
	s_mul_i32 s40, s31, s13
	s_mul_hi_u32 s41, s30, s13
	s_add_i32 s41, s41, s40
	s_mul_i32 s13, s30, s13
	s_add_u32 s42, s28, s13
	s_addc_u32 s43, s29, s41

; #define PG8_STAGE(bufoff, gbase, voff) do { _Pragma("unroll") for (int _i = 0; _i < 2; ++_i) \
;         __builtin_amdgcn_global_load_lds((const unsigned*)((const char*)(gbase) + (voff)[_i]), (PG8_LAS unsigned*)(lds + (bufoff) + ldsw + _i * 8192), 16, 0, 0); } while (0)
; #define PG8_LDA(dst, b, h) do { _Pragma("unroll") for (int m = 0; m < 4; ++m) _Pragma("unroll") for (int k = 0; k < 2; ++k) dst[m][k] = *(const PG8_LAS bf16x8*)(lds + PG8_SA(b, h) + aoff + m * 2048 + k * 1024); } while (0)
; #define PG8_LDB(dst, b, h) do { _Pragma("unroll") for (int n = 0; n < 2; ++n) _Pragma("unroll") for (int k = 0; k < 2; ++k) dst[n][k] = *(const PG8_LAS bf16x8*)(lds + PG8_SB(b, h) + boff + n * 2048 + k * 1024); } while (0)
; #define PG8_MMA(ai, bj, At, Bt) do { __builtin_amdgcn_s_setprio(1); _Pragma("unroll") for (int m = 0; m < 4; ++m) _Pragma("unroll") for (int n = 0; n < 2; ++n) _Pragma("unroll") for (int k = 0; k < 2; ++k) \
;         acc[ai][bj][m][n] = __builtin_amdgcn_mfma_f32_16x16x32_bf16(Bt[n][k], At[m][k], acc[ai][bj][m][n], 0, 0, 0); __builtin_amdgcn_s_setprio(0); } while (0)
; #define PG8_WAIT_V(n) asm volatile("s_waitcnt vmcnt(" #n ")" ::: "memory")
; #define PG8_WAIT_L(n) asm volatile("s_waitcnt lgkmcnt(" #n ")" ::: "memory")
; #define PG8_BAR __builtin_amdgcn_s_barrier()
; template <class Epi, class Sched, bool ALIGN_EPI = false, bool SP2 = false>
; __device__ __forceinline__ void gemm_phase(PG8_LAS unsigned char* lds, const Gemm g, const Sched& S, const Epi& E) {
;     ...
;             const char* a1 = cA + (size_t)(t + 1) * kstep;
;             const char* a2 = last ? nA : cA + (size_t)(t + 2) * kstep; const char* b2 = last ? nB : cB + (size_t)(t + 2) * kstep;
;             const char* a3 = a2 + (last ? knext : kstep); const char* b3 = b2 + (last ? knext : kstep);
;             if (last && has_next) S.a_ready(nxt);
;             if constexpr (SP2) {
;             PG8_LDB(B0, 0, 0); PG8_LDB(B1, 0, 1); PG8_SCHED; PG8_LDA(At, 0, 0); PG8_STAGE(PG8_SA(1, 1), a1 + hstep, voffA);
;             PG8_WAIT_V(8); PG8_WAIT_L(0); PG8_BAR; PG8_MMA(0, 0, At, B0); PG8_MMA(0, 1, At, B1); PG8_BAR; PG8_SCHED;
;             PG8_LDA(At, 0, 1); PG8_STAGE(PG8_SB(0, 0), b2, voffB); PG8_STAGE(PG8_SB(0, 1), b2 + hstep, voffB); PG8_STAGE(PG8_SA(0, 0), a2, voffA);
;             PG8_WAIT_V(8); PG8_WAIT_L(0); PG8_BAR; PG8_MMA(1, 0, At, B0); PG8_MMA(1, 1, At, B1); PG8_BAR; PG8_SCHED;
.LBB0_908:
	s_add_i32 s17, 0, 0x10000
	s_add_i32 s19, 0, 0x14000
	v_add_u32_e32 v148, s17, v187
	v_add_u32_e32 v190, s19, v187
	ds_read_b128 v[96:99], v148
	ds_read_b128 v[100:103], v148 offset:1024
	ds_read_b128 v[144:147], v148 offset:2048
	ds_read_b128 v[148:151], v148 offset:3072
	ds_read_b128 v[174:177], v190
	ds_read_b128 v[178:181], v190 offset:1024
	ds_read_b128 v[182:185], v190 offset:2048
	ds_read_b128 v[190:193], v190 offset:3072
	s_add_i32 s11, s11, 2
	v_lshl_add_u64 v[230:231], v[82:83], 0, v[166:167]
	s_add_i32 m0, s35, 0xc000
	ds_read_b128 v[198:201], v189
	ds_read_b128 v[202:205], v189 offset:1024
	ds_read_b128 v[206:209], v189 offset:2048
	ds_read_b128 v[210:213], v189 offset:3072
	ds_read_b128 v[214:217], v189 offset:4096
	ds_read_b128 v[218:221], v189 offset:5120
	ds_read_b128 v[222:225], v189 offset:6144
	ds_read_b128 v[226:229], v189 offset:7168
	global_load_lds_dwordx4 v[230:231], off
	v_lshl_add_u64 v[230:231], v[82:83], 0, v[168:169]
	s_add_i32 m0, s35, 0xe000
	s_nop 0
	global_load_lds_dwordx4 v[230:231], off
	s_waitcnt vmcnt(8)
	s_waitcnt lgkmcnt(0)
	s_barrier
	s_setprio 1
	s_waitcnt lgkmcnt(0)
	v_mfma_f32_16x16x32_bf16 v[140:143], v[96:99], v[198:201], v[140:143]
	v_mfma_f32_16x16x32_bf16 v[136:139], v[144:147], v[198:201], v[136:139]
	v_mfma_f32_16x16x32_bf16 v[124:127], v[96:99], v[206:209], v[124:127]
	v_mfma_f32_16x16x32_bf16 v[120:123], v[144:147], v[206:209], v[120:123]
	v_mfma_f32_16x16x32_bf16 v[108:111], v[96:99], v[214:217], v[108:111]
	v_mfma_f32_16x16x32_bf16 v[104:107], v[144:147], v[214:217], v[104:107]
	v_mfma_f32_16x16x32_bf16 v[76:79], v[96:99], v[222:225], v[76:79]
	v_mfma_f32_16x16x32_bf16 v[72:75], v[144:147], v[222:225], v[72:75]
	v_mfma_f32_16x16x32_bf16 v[140:143], v[100:103], v[202:205], v[140:143]
	v_mfma_f32_16x16x32_bf16 v[136:139], v[148:151], v[202:205], v[136:139]
	v_mfma_f32_16x16x32_bf16 v[124:127], v[100:103], v[210:213], v[124:127]
	v_mfma_f32_16x16x32_bf16 v[120:123], v[148:151], v[210:213], v[120:123]
	v_mfma_f32_16x16x32_bf16 v[108:111], v[100:103], v[218:221], v[108:111]
	v_mfma_f32_16x16x32_bf16 v[104:107], v[148:151], v[218:221], v[104:107]
	v_mfma_f32_16x16x32_bf16 v[76:79], v[100:103], v[226:229], v[76:79]
	v_mfma_f32_16x16x32_bf16 v[72:75], v[148:151], v[226:229], v[72:75]
	s_setprio 0
	s_setprio 1
	v_mfma_f32_16x16x32_bf16 v[132:135], v[174:177], v[198:201], v[132:135]
	v_mfma_f32_16x16x32_bf16 v[128:131], v[182:185], v[198:201], v[128:131]
	v_mfma_f32_16x16x32_bf16 v[116:119], v[174:177], v[206:209], v[116:119]
	v_mfma_f32_16x16x32_bf16 v[112:115], v[182:185], v[206:209], v[112:115]
	v_mfma_f32_16x16x32_bf16 v[92:95], v[174:177], v[214:217], v[92:95]
	v_mfma_f32_16x16x32_bf16 v[84:87], v[182:185], v[214:217], v[84:87]
	v_mfma_f32_16x16x32_bf16 v[68:71], v[174:177], v[222:225], v[68:71]
	v_mfma_f32_16x16x32_bf16 v[64:67], v[182:185], v[222:225], v[64:67]
	v_mfma_f32_16x16x32_bf16 v[132:135], v[178:181], v[202:205], v[132:135]
	v_mfma_f32_16x16x32_bf16 v[128:131], v[190:193], v[202:205], v[128:131]
	v_mfma_f32_16x16x32_bf16 v[116:119], v[178:181], v[210:213], v[116:119]
	v_mfma_f32_16x16x32_bf16 v[112:115], v[190:193], v[210:213], v[112:115]
	v_mfma_f32_16x16x32_bf16 v[92:95], v[178:181], v[218:221], v[92:95]
	v_mfma_f32_16x16x32_bf16 v[84:87], v[190:193], v[218:221], v[84:87]
	v_mfma_f32_16x16x32_bf16 v[68:71], v[178:181], v[226:229], v[68:71]
	v_mfma_f32_16x16x32_bf16 v[64:67], v[190:193], v[226:229], v[64:67]
	s_setprio 0
	s_barrier
	s_add_i32 s17, s17, s30
	v_lshl_add_u64 v[230:231], v[88:89], 0, v[154:155]
	s_mov_b32 m0, s17
	ds_read_b128 v[198:201], v189 offset:16384
	ds_read_b128 v[202:205], v189 offset:17408
	ds_read_b128 v[206:209], v189 offset:18432
	ds_read_b128 v[210:213], v189 offset:19456
	ds_read_b128 v[214:217], v189 offset:20480
	ds_read_b128 v[218:221], v189 offset:21504
	ds_read_b128 v[222:225], v189 offset:22528
	ds_read_b128 v[226:229], v189 offset:23552
	global_load_lds_dwordx4 v[230:231], off
	v_lshl_add_u64 v[232:233], v[88:89], 0, v[164:165]
	s_add_i32 m0, s17, 0x2000
	v_lshl_add_u64 v[234:235], v[88:89], 0, s[80:81]
	s_add_i32 s17, s19, s30
	global_load_lds_dwordx4 v[232:233], off
	v_lshl_add_u64 v[236:237], v[234:235], 0, v[154:155]
	s_mov_b32 m0, s17
	v_lshl_add_u64 v[234:235], v[234:235], 0, v[164:165]
	global_load_lds_dwordx4 v[236:237], off
	s_add_i32 m0, s17, 0x2000
	v_lshl_add_u64 v[236:237], v[90:91], 0, v[162:163]
	global_load_lds_dwordx4 v[234:235], off
	v_lshl_add_u64 v[234:235], v[90:91], 0, v[160:161]
	s_mov_b32 m0, s35
	s_nop 0
	global_load_lds_dwordx4 v[234:235], off
	s_mov_b32 m0, s36
	s_nop 0
	global_load_lds_dwordx4 v[236:237], off
	s_waitcnt vmcnt(8)
	s_waitcnt lgkmcnt(0)
	s_barrier
; #define PG8_STAGE(bufoff, gbase, voff) do { _Pragma("unroll") for (int _i = 0; _i < 2; ++_i) \
;         __builtin_amdgcn_global_load_lds((const unsigned*)((const char*)(gbase) + (voff)[_i]), (PG8_LAS unsigned*)(lds + (bufoff) + ldsw + _i * 8192), 16, 0, 0); } while (0)
; #define PG8_LDA(dst, b, h) do { _Pragma("unroll") for (int m = 0; m < 4; ++m) _Pragma("unroll") for (int k = 0; k < 2; ++k) dst[m][k] = *(const PG8_LAS bf16x8*)(lds + PG8_SA(b, h) + aoff + m * 2048 + k * 1024); } while (0)
; #define PG8_LDB(dst, b, h) do { _Pragma("unroll") for (int n = 0; n < 2; ++n) _Pragma("unroll") for (int k = 0; k < 2; ++k) dst[n][k] = *(const PG8_LAS bf16x8*)(lds + PG8_SB(b, h) + boff + n * 2048 + k * 1024); } while (0)
; #define PG8_MMA(ai, bj, At, Bt) do { __builtin_amdgcn_s_setprio(1); _Pragma("unroll") for (int m = 0; m < 4; ++m) _Pragma("unroll") for (int n = 0; n < 2; ++n) _Pragma("unroll") for (int k = 0; k < 2; ++k) \
;         acc[ai][bj][m][n] = __builtin_amdgcn_mfma_f32_16x16x32_bf16(Bt[n][k], At[m][k], acc[ai][bj][m][n], 0, 0, 0); __builtin_amdgcn_s_setprio(0); } while (0)
; #define PG8_WAIT_V(n) asm volatile("s_waitcnt vmcnt(" #n ")" ::: "memory")
; #define PG8_WAIT_L(n) asm volatile("s_waitcnt lgkmcnt(" #n ")" ::: "memory")
; #define PG8_BAR __builtin_amdgcn_s_barrier()
; #define PG8_SCHED __builtin_amdgcn_sched_barrier(0)
; template <class Epi, class Sched, bool ALIGN_EPI = false, bool SP2 = false>
; __device__ __forceinline__ void gemm_phase(PG8_LAS unsigned char* lds, const Gemm g, const Sched& S, const Epi& E) {
;     ...
;             PG8_WAIT_V(8); PG8_WAIT_L(0); PG8_BAR; PG8_MMA(1, 0, At, B0); PG8_MMA(1, 1, At, B1); PG8_BAR; PG8_SCHED;
;             PG8_LDB(B0, 1, 0); PG8_LDB(B1, 1, 1); PG8_SCHED; PG8_LDA(At, 1, 0); PG8_STAGE(PG8_SA(0, 1), a2 + hstep, voffA);
;             PG8_WAIT_V(8); PG8_WAIT_L(0); PG8_BAR; PG8_MMA(0, 0, At, B0); PG8_MMA(0, 1, At, B1); PG8_BAR; PG8_SCHED;
	s_setprio 1
	s_waitcnt lgkmcnt(0)
	v_mfma_f32_16x16x32_bf16 v[60:63], v[96:99], v[198:201], v[60:63]
	v_mfma_f32_16x16x32_bf16 v[56:59], v[144:147], v[198:201], v[56:59]
	v_mfma_f32_16x16x32_bf16 v[44:47], v[96:99], v[206:209], v[44:47]
	v_mfma_f32_16x16x32_bf16 v[40:43], v[144:147], v[206:209], v[40:43]
	v_mfma_f32_16x16x32_bf16 v[28:31], v[96:99], v[214:217], v[28:31]
	v_mfma_f32_16x16x32_bf16 v[24:27], v[144:147], v[214:217], v[24:27]
	v_mfma_f32_16x16x32_bf16 v[12:15], v[96:99], v[222:225], v[12:15]
	v_mfma_f32_16x16x32_bf16 v[8:11], v[144:147], v[222:225], v[8:11]
	v_mfma_f32_16x16x32_bf16 v[60:63], v[100:103], v[202:205], v[60:63]
	v_mfma_f32_16x16x32_bf16 v[56:59], v[148:151], v[202:205], v[56:59]
	v_mfma_f32_16x16x32_bf16 v[44:47], v[100:103], v[210:213], v[44:47]
	v_mfma_f32_16x16x32_bf16 v[40:43], v[148:151], v[210:213], v[40:43]
	v_mfma_f32_16x16x32_bf16 v[28:31], v[100:103], v[218:221], v[28:31]
	v_mfma_f32_16x16x32_bf16 v[24:27], v[148:151], v[218:221], v[24:27]
	v_mfma_f32_16x16x32_bf16 v[12:15], v[100:103], v[226:229], v[12:15]
	v_mfma_f32_16x16x32_bf16 v[8:11], v[148:151], v[226:229], v[8:11]
	s_setprio 0
	s_setprio 1
	v_mfma_f32_16x16x32_bf16 v[52:55], v[174:177], v[198:201], v[52:55]
	v_mfma_f32_16x16x32_bf16 v[48:51], v[182:185], v[198:201], v[48:51]
	v_mfma_f32_16x16x32_bf16 v[36:39], v[174:177], v[206:209], v[36:39]
	v_mfma_f32_16x16x32_bf16 v[32:35], v[182:185], v[206:209], v[32:35]
	v_mfma_f32_16x16x32_bf16 v[20:23], v[174:177], v[214:217], v[20:23]
	v_mfma_f32_16x16x32_bf16 v[16:19], v[182:185], v[214:217], v[16:19]
	v_mfma_f32_16x16x32_bf16 v[4:7], v[174:177], v[222:225], v[4:7]
	v_mfma_f32_16x16x32_bf16 v[0:3], v[182:185], v[222:225], v[0:3]
	v_mfma_f32_16x16x32_bf16 v[52:55], v[178:181], v[202:205], v[52:55]
	v_mfma_f32_16x16x32_bf16 v[48:51], v[190:193], v[202:205], v[48:51]
	v_mfma_f32_16x16x32_bf16 v[36:39], v[178:181], v[210:213], v[36:39]
	v_mfma_f32_16x16x32_bf16 v[32:35], v[190:193], v[210:213], v[32:35]
	v_mfma_f32_16x16x32_bf16 v[20:23], v[178:181], v[218:221], v[20:23]
	v_mfma_f32_16x16x32_bf16 v[16:19], v[190:193], v[218:221], v[16:19]
	v_mfma_f32_16x16x32_bf16 v[4:7], v[178:181], v[226:229], v[4:7]
	v_mfma_f32_16x16x32_bf16 v[0:3], v[190:193], v[226:229], v[0:3]
	s_setprio 0
	s_barrier
	s_add_i32 s17, 0, 0x18000
	s_add_i32 s19, 0, 0x1c000
	v_add_u32_e32 v148, s17, v187
	v_add_u32_e32 v190, s19, v187
	ds_read_b128 v[96:99], v148
	ds_read_b128 v[100:103], v148 offset:1024
	ds_read_b128 v[144:147], v148 offset:2048
	ds_read_b128 v[148:151], v148 offset:3072
	ds_read_b128 v[174:177], v190
	ds_read_b128 v[178:181], v190 offset:1024
	ds_read_b128 v[182:185], v190 offset:2048
	ds_read_b128 v[190:193], v190 offset:3072
	v_lshl_add_u64 v[90:91], v[90:91], 0, s[80:81]
	s_mov_b32 m0, s37
	v_lshl_add_u64 v[238:239], v[90:91], 0, v[160:161]
	ds_read_b128 v[198:201], v189 offset:32768
	ds_read_b128 v[202:205], v189 offset:33792
	ds_read_b128 v[206:209], v189 offset:34816
	ds_read_b128 v[210:213], v189 offset:35840
	ds_read_b128 v[214:217], v189 offset:36864
	ds_read_b128 v[218:221], v189 offset:37888
	ds_read_b128 v[222:225], v189 offset:38912
	ds_read_b128 v[226:229], v189 offset:39936
	global_load_lds_dwordx4 v[238:239], off
	v_lshl_add_u64 v[90:91], v[90:91], 0, v[162:163]
	s_mov_b32 m0, s38
	s_nop 0
	global_load_lds_dwordx4 v[90:91], off
	s_waitcnt vmcnt(8)
	s_waitcnt lgkmcnt(0)
	s_barrier
	s_setprio 1
	s_waitcnt lgkmcnt(0)
	v_mfma_f32_16x16x32_bf16 v[140:143], v[96:99], v[198:201], v[140:143]
	v_mfma_f32_16x16x32_bf16 v[136:139], v[144:147], v[198:201], v[136:139]
	v_mfma_f32_16x16x32_bf16 v[124:127], v[96:99], v[206:209], v[124:127]
	v_mfma_f32_16x16x32_bf16 v[120:123], v[144:147], v[206:209], v[120:123]
	v_mfma_f32_16x16x32_bf16 v[108:111], v[96:99], v[214:217], v[108:111]
	v_mfma_f32_16x16x32_bf16 v[104:107], v[144:147], v[214:217], v[104:107]
	v_mfma_f32_16x16x32_bf16 v[76:79], v[96:99], v[222:225], v[76:79]
	v_mfma_f32_16x16x32_bf16 v[72:75], v[144:147], v[222:225], v[72:75]
	v_mfma_f32_16x16x32_bf16 v[140:143], v[100:103], v[202:205], v[140:143]
	v_mfma_f32_16x16x32_bf16 v[136:139], v[148:151], v[202:205], v[136:139]
	v_mfma_f32_16x16x32_bf16 v[124:127], v[100:103], v[210:213], v[124:127]
	v_mfma_f32_16x16x32_bf16 v[120:123], v[148:151], v[210:213], v[120:123]
	v_mfma_f32_16x16x32_bf16 v[108:111], v[100:103], v[218:221], v[108:111]
	v_mfma_f32_16x16x32_bf16 v[104:107], v[148:151], v[218:221], v[104:107]
	v_mfma_f32_16x16x32_bf16 v[76:79], v[100:103], v[226:229], v[76:79]
	v_mfma_f32_16x16x32_bf16 v[72:75], v[148:151], v[226:229], v[72:75]
	s_setprio 0
	s_setprio 1
	v_mfma_f32_16x16x32_bf16 v[132:135], v[174:177], v[198:201], v[132:135]
	v_mfma_f32_16x16x32_bf16 v[128:131], v[182:185], v[198:201], v[128:131]
	v_mfma_f32_16x16x32_bf16 v[116:119], v[174:177], v[206:209], v[116:119]
	v_mfma_f32_16x16x32_bf16 v[112:115], v[182:185], v[206:209], v[112:115]
	v_mfma_f32_16x16x32_bf16 v[90:93], v[174:177], v[214:217], v[92:95]
	v_mfma_f32_16x16x32_bf16 v[84:87], v[182:185], v[214:217], v[84:87]
	v_mfma_f32_16x16x32_bf16 v[68:71], v[174:177], v[222:225], v[68:71]
	v_mfma_f32_16x16x32_bf16 v[64:67], v[182:185], v[222:225], v[64:67]
	v_mfma_f32_16x16x32_bf16 v[132:135], v[178:181], v[202:205], v[132:135]
	v_mfma_f32_16x16x32_bf16 v[128:131], v[190:193], v[202:205], v[128:131]
	v_mfma_f32_16x16x32_bf16 v[116:119], v[178:181], v[210:213], v[116:119]
	v_mfma_f32_16x16x32_bf16 v[112:115], v[190:193], v[210:213], v[112:115]
	v_mfma_f32_16x16x32_bf16 v[92:95], v[178:181], v[218:221], v[90:93]
	v_mfma_f32_16x16x32_bf16 v[84:87], v[190:193], v[218:221], v[84:87]
	v_mfma_f32_16x16x32_bf16 v[68:71], v[178:181], v[226:229], v[68:71]
	v_mfma_f32_16x16x32_bf16 v[64:67], v[190:193], v[226:229], v[64:67]
	s_setprio 0
	s_barrier
; #define PG8_STAGE(bufoff, gbase, voff) do { _Pragma("unroll") for (int _i = 0; _i < 2; ++_i) \
;         __builtin_amdgcn_global_load_lds((const unsigned*)((const char*)(gbase) + (voff)[_i]), (PG8_LAS unsigned*)(lds + (bufoff) + ldsw + _i * 8192), 16, 0, 0); } while (0)
; #define PG8_LDA(dst, b, h) do { _Pragma("unroll") for (int m = 0; m < 4; ++m) _Pragma("unroll") for (int k = 0; k < 2; ++k) dst[m][k] = *(const PG8_LAS bf16x8*)(lds + PG8_SA(b, h) + aoff + m * 2048 + k * 1024); } while (0)
; #define PG8_WAIT_V(n) asm volatile("s_waitcnt vmcnt(" #n ")" ::: "memory")
; #define PG8_WAIT_L(n) asm volatile("s_waitcnt lgkmcnt(" #n ")" ::: "memory")
; template <class Epi, class Sched, bool ALIGN_EPI = false, bool SP2 = false>
; __device__ __forceinline__ void gemm_phase(PG8_LAS unsigned char* lds, const Gemm g, const Sched& S, const Epi& E) {
;     ...
;         for (int t = 0; t < nt; t += 2) {
;             const bool last = (t == nt - 2);
;             const char* a1 = cA + (size_t)(t + 1) * kstep;
;             const char* a2 = last ? nA : cA + (size_t)(t + 2) * kstep; const char* b2 = last ? nB : cB + (size_t)(t + 2) * kstep;
;             const char* a3 = a2 + (last ? knext : kstep); const char* b3 = b2 + (last ? knext : kstep);
;             if (last && has_next) S.a_ready(nxt);
;             if constexpr (SP2) {
;             PG8_LDB(B0, 0, 0); PG8_LDB(B1, 0, 1); PG8_SCHED; PG8_LDA(At, 0, 0); PG8_STAGE(PG8_SA(1, 1), a1 + hstep, voffA);
;             PG8_WAIT_V(8); PG8_WAIT_L(0); PG8_BAR; PG8_MMA(0, 0, At, B0); PG8_MMA(0, 1, At, B1); PG8_BAR; PG8_SCHED;
;             PG8_LDA(At, 0, 1); PG8_STAGE(PG8_SB(0, 0), b2, voffB); PG8_STAGE(PG8_SB(0, 1), b2 + hstep, voffB); PG8_STAGE(PG8_SA(0, 0), a2, voffA);
;             PG8_WAIT_V(8); PG8_WAIT_L(0); PG8_BAR; PG8_MMA(1, 0, At, B0); PG8_MMA(1, 1, At, B1); PG8_BAR; PG8_SCHED;
;             PG8_LDB(B0, 1, 0); PG8_LDB(B1, 1, 1); PG8_SCHED; PG8_LDA(At, 1, 0); PG8_STAGE(PG8_SA(0, 1), a2 + hstep, voffA);
;             PG8_WAIT_V(8); PG8_WAIT_L(0); PG8_BAR; PG8_MMA(0, 0, At, B0); PG8_MMA(0, 1, At, B1); PG8_BAR; PG8_SCHED;
;             PG8_LDA(At, 1, 1); PG8_STAGE(PG8_SB(1, 0), b3, voffB); PG8_STAGE(PG8_SB(1, 1), b3 + hstep, voffB); PG8_STAGE(PG8_SA(1, 0), a3, voffA);
;             PG8_WAIT_V(8); PG8_WAIT_L(0); PG8_BAR; PG8_MMA(1, 0, At, B0); PG8_MMA(1, 1, At, B1); PG8_BAR; PG8_SCHED;
	s_add_i32 s17, s17, s30
	v_lshl_add_u64 v[90:91], v[230:231], 0, s[84:85]
	s_mov_b32 m0, s17
	ds_read_b128 v[198:201], v189 offset:49152
	ds_read_b128 v[202:205], v189 offset:50176
	ds_read_b128 v[206:209], v189 offset:51200
	ds_read_b128 v[210:213], v189 offset:52224
	ds_read_b128 v[214:217], v189 offset:53248
	ds_read_b128 v[218:221], v189 offset:54272
	ds_read_b128 v[222:225], v189 offset:55296
	ds_read_b128 v[226:229], v189 offset:56320
	global_load_lds_dwordx4 v[90:91], off
	v_lshl_add_u64 v[90:91], v[232:233], 0, s[84:85]
	s_add_i32 m0, s17, 0x2000
	v_lshl_add_u64 v[88:89], v[88:89], 0, s[86:87]
	s_add_i32 s17, s19, s30
	global_load_lds_dwordx4 v[90:91], off
	v_lshl_add_u64 v[90:91], v[88:89], 0, v[154:155]
	s_mov_b32 m0, s17
	v_lshl_add_u64 v[88:89], v[88:89], 0, v[164:165]
	global_load_lds_dwordx4 v[90:91], off
	s_add_i32 m0, s17, 0x2000
	s_nop 0
	global_load_lds_dwordx4 v[88:89], off
	v_lshl_add_u64 v[88:89], v[234:235], 0, s[84:85]
	s_mov_b32 m0, s41
	s_nop 0
	global_load_lds_dwordx4 v[88:89], off
	v_lshl_add_u64 v[88:89], v[236:237], 0, s[84:85]
	s_mov_b32 m0, s42
	s_nop 0
	global_load_lds_dwordx4 v[88:89], off
	s_waitcnt vmcnt(8)
	s_waitcnt lgkmcnt(0)
	s_barrier
	s_setprio 1
	s_waitcnt lgkmcnt(0)
	v_mfma_f32_16x16x32_bf16 v[60:63], v[96:99], v[198:201], v[60:63]
	v_mfma_f32_16x16x32_bf16 v[56:59], v[144:147], v[198:201], v[56:59]
	v_mfma_f32_16x16x32_bf16 v[44:47], v[96:99], v[206:209], v[44:47]
	v_mfma_f32_16x16x32_bf16 v[40:43], v[144:147], v[206:209], v[40:43]
	v_mfma_f32_16x16x32_bf16 v[28:31], v[96:99], v[214:217], v[28:31]
	v_mfma_f32_16x16x32_bf16 v[24:27], v[144:147], v[214:217], v[24:27]
	v_mfma_f32_16x16x32_bf16 v[12:15], v[96:99], v[222:225], v[12:15]
	v_mfma_f32_16x16x32_bf16 v[8:11], v[144:147], v[222:225], v[8:11]
	v_mfma_f32_16x16x32_bf16 v[60:63], v[100:103], v[202:205], v[60:63]
	v_mfma_f32_16x16x32_bf16 v[56:59], v[148:151], v[202:205], v[56:59]
	v_mfma_f32_16x16x32_bf16 v[44:47], v[100:103], v[210:213], v[44:47]
	v_mfma_f32_16x16x32_bf16 v[40:43], v[148:151], v[210:213], v[40:43]
	v_mfma_f32_16x16x32_bf16 v[28:31], v[100:103], v[218:221], v[28:31]
	v_mfma_f32_16x16x32_bf16 v[24:27], v[148:151], v[218:221], v[24:27]
	v_mfma_f32_16x16x32_bf16 v[12:15], v[100:103], v[226:229], v[12:15]
	v_mfma_f32_16x16x32_bf16 v[8:11], v[148:151], v[226:229], v[8:11]
	s_setprio 0
	s_setprio 1
	v_mfma_f32_16x16x32_bf16 v[52:55], v[174:177], v[198:201], v[52:55]
	v_mfma_f32_16x16x32_bf16 v[48:51], v[182:185], v[198:201], v[48:51]
	v_mfma_f32_16x16x32_bf16 v[36:39], v[174:177], v[206:209], v[36:39]
	v_mfma_f32_16x16x32_bf16 v[32:35], v[182:185], v[206:209], v[32:35]
	v_mfma_f32_16x16x32_bf16 v[20:23], v[174:177], v[214:217], v[20:23]
	v_mfma_f32_16x16x32_bf16 v[16:19], v[182:185], v[214:217], v[16:19]
	v_mfma_f32_16x16x32_bf16 v[4:7], v[174:177], v[222:225], v[4:7]
	v_mfma_f32_16x16x32_bf16 v[0:3], v[182:185], v[222:225], v[0:3]
	v_mfma_f32_16x16x32_bf16 v[52:55], v[178:181], v[202:205], v[52:55]
	v_mfma_f32_16x16x32_bf16 v[48:51], v[190:193], v[202:205], v[48:51]
	v_mfma_f32_16x16x32_bf16 v[36:39], v[178:181], v[210:213], v[36:39]
	v_mfma_f32_16x16x32_bf16 v[32:35], v[190:193], v[210:213], v[32:35]
	v_mfma_f32_16x16x32_bf16 v[20:23], v[178:181], v[218:221], v[20:23]
	v_mfma_f32_16x16x32_bf16 v[16:19], v[190:193], v[218:221], v[16:19]
	v_mfma_f32_16x16x32_bf16 v[4:7], v[178:181], v[226:229], v[4:7]
	v_mfma_f32_16x16x32_bf16 v[0:3], v[190:193], v[226:229], v[0:3]
	s_setprio 0
	v_lshl_add_u64 v[80:81], v[80:81], 0, s[88:89]
	s_cmp_ge_i32 s11, s1
	v_lshl_add_u64 v[82:83], v[82:83], 0, s[88:89]
	s_cbranch_scc1 .Lrot_r909_exit
	s_cmp_lg_u32 s9, s11
	s_cselect_b64 s[24:25], -1, 0
	s_cmp_eq_u32 s9, s11
	v_mov_b64_e32 v[90:91], v[170:171]
	s_cbranch_scc1 .Lrot_r909_911
	s_mov_b32 s48, 0xffefff80
	s_mov_b32 s49, -1
	v_lshl_add_u64 v[90:91], v[82:83], 0, s[48:49]
